# dil-1 attention pass re-tiled: each wave handles 2 tiles of near-consecutive queries (5 key steps instead of 12), partial (m,l,O) exchanged through LDS and merged into the residue-class state; exact s
# speedup vs baseline: 1.0187x; 1.0187x over previous
; __device__ __forceinline__ int opaque_tid() { int t = threadIdx.x; asm volatile("" : "+v"(t)); return t; }
; __device__ __forceinline__ void attn_item(const bf16_t* __restrict__ Z, const bf16_t* __restrict__ KA, const bf16_t* __restrict__ VA, bf16_t* __restrict__ MIX, int S, int it) {
;     const int tid = opaque_tid();
;     const int wave = tid >> 6, lane = tid & 63, qi = lane & 15, g = lane >> 4;
;     const int lgb = (S == 16384) ? 6 : 3;
;     const int pb = it & ((1 << lgb) - 1); const int t1 = it >> lgb; const int head = t1 & 7, seq = t1 >> 3;
;     const int P0 = pb * 256, n0 = pb * 16;
;     const bf16_t* zq = Z + (size_t)seq * S * ZW;
;     const bf16_t* ka = KA + ((size_t)head * MG + (size_t)seq * S) * 64; const bf16_t* va = VA + ((size_t)head * MG + (size_t)seq * S) * 64;
;     bf16_t* Kt = (bf16_t*)g_lds;
;     bf16_t* Vt = (bf16_t*)(g_lds + 57600);
;     bf16_t* Vs = (bf16_t*)g_lds + wave * (32 * 68);
;     int rt[2]; rt[0] = 4 * (wave >> 1) + (wave & 1); rt[1] = rt[0] + 2;
;     bf16x8 q0[2], q1[2]; float m[2] = {-1e30f, -1e30f}, lsum[2] = {0.f, 0.f}; f32x4 O[2][4] = {};
; #pragma unroll
;     for (int ti = 0; ti < 2; ++ti) { const bf16_t* qp = zq + (size_t)(P0 + rt[ti] + 16 * qi) * ZW + ZC_AQ + head * 64 + 8 * g; q0[ti] = *(const bf16x8*)qp; q1[ti] = *(const bf16x8*)(qp + 32); }
.LBB0_400:
	v_readlane_b32 s2, v254, 23
	s_or_b32 s3, s5, s2
	v_readlane_b32 s6, v255, 30
	s_lshr_b32 s3, s3, s6
	v_readlane_b32 s2, v255, 36
	s_and_b32 s15, s3, 7
	s_lshr_b32 s3, s3, 3
	v_readlane_b32 s6, v255, 31
	s_and_b32 s2, s5, s2
	s_lshl_b32 s13, s3, s6
	s_lshl_b32 s12, s2, 8
	s_mul_i32 s6, s13, 0x1c00
	v_readlane_b32 s18, v252, 51
	s_mul_hi_u32 s3, s13, 0x1c00
	v_readlane_b32 s19, v252, 52
	s_add_u32 s18, s18, s6
	s_addc_u32 s3, s19, s3
	s_lshl_b32 s6, s15, 21
	s_lshl_b32 s7, s13, 6
	s_add_i32 s7, s7, s6
	s_lshl_b32 s20, s7, 1
	v_readlane_b32 s6, v252, 57
	v_mov_b32_e32 v187, v176
	s_add_u32 s6, s6, s20
	v_readlane_b32 s7, v252, 58
	s_addc_u32 s7, s7, 0
	v_ashrrev_i32_e32 v14, 6, v187
	v_and_b32_e32 v215, 15, v187
	v_ashrrev_i32_e32 v217, 5, v187
	s_lshl_b32 s14, s15, 6
	s_lshl_b32 s15, s15, 7
	v_and_b32_e32 v216, -4, v217
	v_and_b32_e32 v211, 1, v14
	v_lshlrev_b32_e32 v181, 4, v215
	s_add_u32 s18, s18, s15
	v_or_b32_e32 v182, v216, v211
	v_or_b32_e32 v4, s12, v181
	s_addc_u32 s19, s3, 0
	v_and_b32_e32 v178, 48, v187
	v_lshl_add_u64 v[0:1], s[18:19], 0, v[178:179]
	v_add_u32_e32 v2, v4, v182
	s_movk_i32 s3, 0x1c00
	v_or_b32_e32 v180, 2, v182
	v_mad_i64_i32 v[2:3], s[18:19], v2, s3, v[0:1]
	global_load_dwordx4 v[40:43], v[2:3], off
	global_load_dwordx4 v[44:47], v[2:3], off offset:64
	v_add_u32_e32 v2, v180, v4
	v_mad_i64_i32 v[4:5], s[18:19], v2, s3, v[0:1]
	v_lshrrev_b32_e32 v244, 1, v215
	v_and_b32_e32 v245, 1, v215
	v_lshl_add_u32 v244, v244, 2, v245
	v_lshl_add_u32 v244, v14, 5, v244
	v_add_u32_e32 v244, s12, v244
	v_mad_i64_i32 v[246:247], s[18:19], v244, s3, v[0:1]
	v_add_u32_e32 v244, 2, v244
	global_load_dwordx4 v[228:231], v[246:247], off
	global_load_dwordx4 v[232:235], v[246:247], off offset:64
	v_mad_i64_i32 v[246:247], s[18:19], v244, s3, v[0:1]
	s_nop 1
	global_load_dwordx4 v[236:239], v[246:247], off
	global_load_dwordx4 v[240:243], v[246:247], off offset:64
	s_lshl_b32 s3, s2, 4
	v_readlane_b32 s15, v252, 59
	s_add_u32 s94, s15, s20
	v_readlane_b32 s15, v252, 60
	s_addc_u32 s95, s15, 0
	v_ashrrev_i32_e32 v8, 9, v187
	s_sub_i32 s15, s3, 64
	v_add_u32_e32 v12, s15, v8
	v_lshlrev_b32_e32 v8, 1, v187
	v_and_b32_e32 v212, 3, v187
	v_and_or_b32 v220, v8, 24, v212
	v_add_u32_e32 v8, v220, v12
	v_max_i32_e32 v9, 0, v8
	v_readlane_b32 s15, v255, 37
	v_max_i32_e32 v8, -4, v8
	v_add_u32_e32 v8, 4, v8
	v_min_u32_e32 v9, s15, v9
	v_bitop3_b32 v15, v216, 13, v211 bitop3:0xc8
	v_min_u32_e32 v10, s15, v8
	v_lshlrev_b32_e32 v16, 4, v9
	v_or_b32_e32 v8, v16, v15
	v_mov_b32_e32 v9, v179
	v_lshlrev_b32_e32 v17, 4, v10
	v_lshlrev_b64 v[8:9], 7, v[8:9]
	v_or_b32_e32 v10, v17, v15
	v_mov_b32_e32 v11, v179
	v_lshl_add_u64 v[8:9], s[6:7], 0, v[8:9]
	v_lshlrev_b64 v[10:11], 7, v[10:11]
	v_lshl_add_u64 v[8:9], v[8:9], 0, v[178:179]
	v_lshl_add_u64 v[10:11], s[6:7], 0, v[10:11]
	global_load_dwordx4 v[0:3], v[4:5], off
	s_nop 0
	global_load_dwordx4 v[4:7], v[4:5], off offset:64
	v_lshl_add_u64 v[10:11], v[10:11], 0, v[178:179]
	global_load_dwordx4 v[140:143], v[8:9], off
	global_load_dwordx4 v[136:139], v[8:9], off offset:64
	global_load_dwordx4 v[124:127], v[10:11], off
	global_load_dwordx4 v[120:123], v[10:11], off offset:64
	v_bfe_u32 v221, v187, 3, 3
	v_lshlrev_b32_e32 v8, 4, v187
	v_add_u32_e32 v18, v12, v221
	v_and_b32_e32 v8, 0x70, v8
	v_mov_b32_e32 v9, v179
	v_lshl_add_u64 v[188:189], s[94:95], 0, v[8:9]
	v_max_i32_e32 v9, 0, v18
	v_max_i32_e32 v12, -8, v18
	v_min_u32_e32 v9, s15, v9
	v_add_u32_e32 v12, 8, v12
	v_lshlrev_b32_e32 v9, 4, v9
	v_min_u32_e32 v12, s15, v12
	v_or_b32_e32 v10, v9, v15
	v_mov_b32_e32 v11, v179
	v_lshlrev_b32_e32 v19, 4, v12
	v_lshlrev_b64 v[10:11], 7, v[10:11]
	v_or_b32_e32 v12, v19, v15
	v_mov_b32_e32 v13, v179
	v_lshl_add_u64 v[10:11], v[188:189], 0, v[10:11]
	v_lshlrev_b64 v[12:13], 7, v[12:13]
	v_lshl_add_u64 v[12:13], v[188:189], 0, v[12:13]
	global_load_dwordx4 v[132:135], v[10:11], off
	global_load_dwordx4 v[128:131], v[12:13], off
	v_max_i32_e32 v10, -16, v18
	v_add_u32_e32 v10, 16, v10
	v_max_i32_e32 v12, 0xffffffe8, v18
	v_min_u32_e32 v10, s15, v10
	v_add_u32_e32 v12, 24, v12
	v_lshlrev_b32_e32 v20, 4, v10
	v_min_u32_e32 v12, s15, v12
	v_or_b32_e32 v10, v20, v15
	v_mov_b32_e32 v11, v179
	v_lshlrev_b32_e32 v18, 4, v12
	v_lshlrev_b64 v[10:11], 7, v[10:11]
	v_or_b32_e32 v12, v18, v15
	v_mov_b32_e32 v13, v179
	v_lshl_add_u64 v[10:11], v[188:189], 0, v[10:11]
	v_lshlrev_b64 v[12:13], 7, v[12:13]
	v_bitop3_b32 v15, v182, 15, 2 bitop3:0xc8
	v_lshl_add_u64 v[12:13], v[188:189], 0, v[12:13]
	global_load_dwordx4 v[116:119], v[10:11], off
	global_load_dwordx4 v[112:115], v[12:13], off
	v_or_b32_e32 v10, v16, v15
	v_mov_b32_e32 v11, v179
	v_lshlrev_b64 v[10:11], 7, v[10:11]
	v_or_b32_e32 v12, v17, v15
	v_mov_b32_e32 v13, v179
	v_lshl_add_u64 v[10:11], s[6:7], 0, v[10:11]
	v_lshlrev_b64 v[12:13], 7, v[12:13]
	v_lshl_add_u64 v[10:11], v[10:11], 0, v[178:179]
	v_lshl_add_u64 v[12:13], s[6:7], 0, v[12:13]
	v_lshl_add_u64 v[12:13], v[12:13], 0, v[178:179]
	global_load_dwordx4 v[172:175], v[10:11], off
	global_load_dwordx4 v[168:171], v[10:11], off offset:64
	global_load_dwordx4 v[164:167], v[12:13], off
	global_load_dwordx4 v[160:163], v[12:13], off offset:64
	v_or_b32_e32 v10, v9, v15
	v_mov_b32_e32 v11, v179
	v_lshlrev_b64 v[10:11], 7, v[10:11]
	v_or_b32_e32 v12, v19, v15
	v_mov_b32_e32 v13, v179
	v_lshl_add_u64 v[10:11], v[188:189], 0, v[10:11]
	v_lshlrev_b64 v[12:13], 7, v[12:13]
	v_lshl_add_u64 v[12:13], v[188:189], 0, v[12:13]
	global_load_dwordx4 v[156:159], v[10:11], off
	global_load_dwordx4 v[148:151], v[12:13], off
	v_or_b32_e32 v10, v20, v15
	v_mov_b32_e32 v11, v179
	v_lshlrev_b64 v[10:11], 7, v[10:11]
; __device__ __forceinline__ AttnLd attn_load(const bf16_t* __restrict__ ka, const bf16_t* __restrict__ va, int S, int r, int n0, int lane, int f) {
;     int dsh, cb; attn_geom(f, r, n0, dsh, cb);
;     const int qi = lane & 15, g = lane >> 4, rd = r & ((1 << dsh) - 1), ncls = S >> dsh;
;     const int cA = cb + 8 * (qi >> 2) + (qi & 3), cB = cA + 4;
;     const int cAc = min(max(cA, 0), ncls - 1), cBc = min(max(cB, 0), ncls - 1);
;     const bf16_t* kA = ka + (size_t)(rd + (cAc << dsh)) * 64 + 8 * g;
;     const bf16_t* kB = ka + (size_t)(rd + (cBc << dsh)) * 64 + 8 * g;
;     AttnLd L;
;     L.ka0 = *(const bf16x8*)kA; L.ka1 = *(const bf16x8*)(kA + 32); L.kb0 = *(const bf16x8*)kB; L.kb1 = *(const bf16x8*)(kB + 32);
;     const int cv0 = cb + (lane >> 3);
;     const bf16_t* vb = va + 8 * (lane & 7);
;     L.v0 = *(const u32x4*)(vb + (size_t)(rd + (min(max(cv0, 0), ncls - 1) << dsh)) * 64);
;     L.v1 = *(const u32x4*)(vb + (size_t)(rd + (min(max(cv0 + 8, 0), ncls - 1) << dsh)) * 64);
;     L.v2 = *(const u32x4*)(vb + (size_t)(rd + (min(max(cv0 + 16, 0), ncls - 1) << dsh)) * 64);
;     L.v3 = *(const u32x4*)(vb + (size_t)(rd + (min(max(cv0 + 24, 0), ncls - 1) << dsh)) * 64);
; __device__ __forceinline__ void attn_item(const bf16_t* __restrict__ Z, const bf16_t* __restrict__ KA, const bf16_t* __restrict__ VA, bf16_t* __restrict__ MIX, int S, int it) {
;     ...
;     bf16x8 q0[2], q1[2]; float m[2] = {-1e30f, -1e30f}, lsum[2] = {0.f, 0.f}; f32x4 O[2][4] = {};
; #pragma unroll
;     for (int ti = 0; ti < 2; ++ti) { const bf16_t* qp = zq + (size_t)(P0 + rt[ti] + 16 * qi) * ZW + ZC_AQ + head * 64 + 8 * g; q0[ti] = *(const bf16x8*)qp; q1[ti] = *(const bf16x8*)(qp + 32); }
;     {
;         bf16_t* Vs1 = Vs + 8 * (32 * 68);
;         AttnLd cur0 = attn_load(ka, va, S, rt[0], n0, lane, 18), cur1 = attn_load(ka, va, S, rt[1], n0, lane, 18);
; #pragma unroll 1
;         for (int f = 18; f < 23; ++f) {
;             const AttnLd nxt0 = attn_load(ka, va, S, rt[0], n0, lane, f < 22 ? f + 1 : 22), nxt1 = attn_load(ka, va, S, rt[1], n0, lane, f < 22 ? f + 1 : 22);
;             const int cb = n0 - 64 + 32 * (f - 18), ncls = S >> 4, cq = n0 + qi;
;             f32x4 sA0 = {0.f, 0.f, 0.f, 0.f}, sB0 = {0.f, 0.f, 0.f, 0.f}, sA1 = {0.f, 0.f, 0.f, 0.f}, sB1 = {0.f, 0.f, 0.f, 0.f};
	v_or_b32_e32 v12, v18, v15
	v_mov_b32_e32 v13, v179
	v_lshl_add_u64 v[10:11], v[188:189], 0, v[10:11]
	v_lshlrev_b64 v[12:13], 7, v[12:13]
	v_lshl_add_u64 v[12:13], v[188:189], 0, v[12:13]
	global_load_dwordx4 v[152:155], v[10:11], off
	global_load_dwordx4 v[144:147], v[12:13], off
	s_movk_i32 s15, 0x1100
	v_mul_lo_u32 v9, v14, s15
	v_mul_u32_u24_e32 v10, 0x44, v221
	v_bfe_u32 v218, v187, 4, 2
	v_add_u32_e32 v9, 0, v9
	v_lshlrev_b32_e32 v10, 1, v10
	v_add3_u32 v222, v9, v10, v8
	v_mul_u32_u24_e32 v8, 0x220, v218
	v_bfe_u32 v214, v187, 2, 2
	v_lshlrev_b32_e32 v11, 3, v187
	v_lshl_add_u32 v8, v8, 1, v9
	v_mul_u32_u24_e32 v9, 0x44, v214
	v_lshlrev_b32_e32 v186, 3, v218
	v_lshlrev_b32_e32 v219, 1, v9
	v_and_b32_e32 v9, 24, v11
	v_mov_b32_e32 v12, 0
	s_mov_b32 s15, 0
	v_lshl_add_u64 v[190:191], s[6:7], 0, v[178:179]
	v_lshlrev_b32_e32 v213, 2, v215
	v_add3_u32 v223, v8, v219, v9
	v_add_u32_e32 v224, s3, v186
	v_sub_u32_e32 v225, v186, v215
	v_mov_b32_e32 v183, 0xf149f2ca
	s_mov_b32 s18, 19
	v_mov_b32_e32 v13, v12
	v_mov_b32_e32 v14, v12
	v_mov_b32_e32 v15, v12
	v_mov_b32_e32 v20, v12
	v_mov_b32_e32 v21, v12
	v_mov_b32_e32 v22, v12
	v_mov_b32_e32 v23, v12
	v_mov_b32_e32 v8, v12
	v_mov_b32_e32 v9, v12
	v_mov_b32_e32 v10, v12
	v_mov_b32_e32 v11, v12
	v_mov_b32_e32 v16, v12
	v_mov_b32_e32 v17, v12
	v_mov_b32_e32 v18, v12
	v_mov_b32_e32 v19, v12
	v_mov_b32_e32 v36, v12
	v_mov_b32_e32 v37, v12
	v_mov_b32_e32 v38, v12
	v_mov_b32_e32 v39, v12
	v_mov_b32_e32 v32, v12
	v_mov_b32_e32 v33, v12
	v_mov_b32_e32 v34, v12
	v_mov_b32_e32 v35, v12
	v_mov_b32_e32 v24, v12
	v_mov_b32_e32 v25, v12
	v_mov_b32_e32 v26, v12
	v_mov_b32_e32 v27, v12
	v_mov_b32_e32 v28, v12
	v_mov_b32_e32 v29, v12
	v_mov_b32_e32 v30, v12
	v_mov_b32_e32 v31, v12
	v_mov_b32_e32 v184, v12
	v_mov_b32_e32 v185, v12
	v_mov_b32_e32 v177, 0xf149f2ca
.LBB0_401:
	s_cmpk_lg_i32 s15, 0x80
	s_cselect_b32 s19, s18, 22
	s_cmp_lt_u32 s19, 18
	s_cselect_b32 s20, 2, 4
	s_add_i32 s22, s19, -12
	s_cmp_lt_u32 s22, 6
	s_cselect_b32 s22, -12, 0xffffffee
	s_cmp_gt_u32 s19, 11
	s_cselect_b32 s20, s20, 0
	s_cselect_b32 s22, s22, 0
	s_add_i32 s22, s22, s19
	s_lshr_b32 s19, 16, s20
	s_mul_i32 s19, s19, s3
	s_lshl_b32 s22, s22, 5
	s_add_i32 s19, s19, s22
	v_ashrrev_i32_e32 v48, s20, v182
	s_sub_i32 s19, s19, 64
	v_add_u32_e32 v52, s19, v48
	s_lshr_b32 s23, s79, s20
	v_add_u32_e32 v48, v52, v220
	s_lshl_b32 s22, -1, s20
	v_max_i32_e32 v49, 0, v48
	s_add_i32 s23, s23, -1
	v_max_i32_e32 v48, -4, v48
	v_bitop3_b32 v53, v182, s22, v182 bitop3:0x30
	v_min_u32_e32 v49, s23, v49
	v_add_u32_e32 v48, 4, v48
	v_min_u32_e32 v50, s23, v48
	v_lshl_add_u32 v178, v49, s20, v53
	v_lshlrev_b64 v[48:49], 7, v[178:179]
	v_lshl_add_u32 v178, v50, s20, v53
	v_lshlrev_b64 v[50:51], 7, v[178:179]
	v_lshl_add_u64 v[48:49], v[190:191], 0, v[48:49]
	v_lshl_add_u64 v[50:51], v[190:191], 0, v[50:51]
	global_load_dwordx4 v[56:59], v[48:49], off
	global_load_dwordx4 v[60:63], v[48:49], off offset:64
	global_load_dwordx4 v[88:91], v[50:51], off
	global_load_dwordx4 v[92:95], v[50:51], off offset:64
	v_add_u32_e32 v50, v52, v221
	v_max_i32_e32 v48, 0, v50
	v_min_u32_e32 v48, s23, v48
	v_lshl_add_u32 v178, v48, s20, v53
	v_lshlrev_b64 v[48:49], 7, v[178:179]
	v_lshl_add_u64 v[48:49], v[188:189], 0, v[48:49]
	global_load_dwordx4 v[96:99], v[48:49], off
	v_max_i32_e32 v48, -8, v50
	v_add_u32_e32 v48, 8, v48
	v_min_u32_e32 v48, s23, v48
	v_lshl_add_u32 v178, v48, s20, v53
	v_lshlrev_b64 v[48:49], 7, v[178:179]
	v_lshl_add_u64 v[48:49], v[188:189], 0, v[48:49]
	global_load_dwordx4 v[100:103], v[48:49], off
	v_max_i32_e32 v48, -16, v50
	v_add_u32_e32 v48, 16, v48
	v_min_u32_e32 v48, s23, v48
	v_lshl_add_u32 v178, v48, s20, v53
	v_lshlrev_b64 v[48:49], 7, v[178:179]
	v_lshl_add_u64 v[48:49], v[188:189], 0, v[48:49]
	global_load_dwordx4 v[104:107], v[48:49], off
	v_max_i32_e32 v48, 0xffffffe8, v50
	v_add_u32_e32 v48, 24, v48
	v_min_u32_e32 v48, s23, v48
	v_lshl_add_u32 v178, v48, s20, v53
	v_lshlrev_b64 v[48:49], 7, v[178:179]
	v_lshl_add_u64 v[48:49], v[188:189], 0, v[48:49]
	global_load_dwordx4 v[108:111], v[48:49], off
	v_ashrrev_i32_e32 v48, s20, v180
	v_add_u32_e32 v72, s19, v48
	v_add_u32_e32 v48, v72, v220
	v_max_i32_e32 v49, 0, v48
	v_max_i32_e32 v48, -4, v48
	v_bitop3_b32 v84, v180, s22, v180 bitop3:0x30
	v_min_u32_e32 v49, s23, v49
	v_add_u32_e32 v48, 4, v48
	v_add_u32_e32 v85, v72, v221
	v_min_u32_e32 v50, s23, v48
	v_lshl_add_u32 v178, v49, s20, v84
	v_max_i32_e32 v72, 0, v85
	v_max_i32_e32 v76, -8, v85
	v_lshlrev_b64 v[48:49], 7, v[178:179]
	v_lshl_add_u32 v178, v50, s20, v84
	v_min_u32_e32 v72, s23, v72
	v_add_u32_e32 v76, 8, v76
	v_max_i32_e32 v80, -16, v85
	v_lshl_add_u64 v[52:53], v[190:191], 0, v[48:49]
	v_lshlrev_b64 v[48:49], 7, v[178:179]
	v_lshl_add_u32 v178, v72, s20, v84
	v_min_u32_e32 v76, s23, v76
	v_add_u32_e32 v80, 16, v80
	v_max_i32_e32 v85, 0xffffffe8, v85
	v_lshlrev_b64 v[72:73], 7, v[178:179]
	v_lshl_add_u32 v178, v76, s20, v84
	v_min_u32_e32 v80, s23, v80
	v_add_u32_e32 v85, 24, v85
	s_waitcnt vmcnt(21)
	v_mfma_f32_16x16x32_bf16 v[124:127], v[124:127], v[40:43], 0
	v_lshlrev_b64 v[76:77], 7, v[178:179]
	v_lshl_add_u32 v178, v80, s20, v84
	v_min_u32_e32 v85, s23, v85
	v_lshlrev_b64 v[80:81], 7, v[178:179]
	v_lshl_add_u32 v178, v85, s20, v84
	v_lshlrev_b64 v[84:85], 7, v[178:179]
	v_lshl_add_u64 v[68:69], v[190:191], 0, v[48:49]
	v_lshl_add_u64 v[72:73], v[188:189], 0, v[72:73]
	v_lshl_add_u64 v[76:77], v[188:189], 0, v[76:77]
	v_lshl_add_u64 v[80:81], v[188:189], 0, v[80:81]
	v_lshl_add_u64 v[84:85], v[188:189], 0, v[84:85]
	s_waitcnt vmcnt(20)
; #define LDS_FENCE() asm volatile("s_waitcnt lgkmcnt(0)" ::: "memory")
; #define MFMA16(a, b, c) __builtin_amdgcn_mfma_f32_16x16x32_bf16((a), (b), (c), 0, 0, 0)
; __device__ __forceinline__ void attn_item(const bf16_t* __restrict__ Z, const bf16_t* __restrict__ KA, const bf16_t* __restrict__ VA, bf16_t* __restrict__ MIX, int S, int it) {
;     ...
;             sA0 = MFMA16(cur0.ka0, q0[0], sA0); sA1 = MFMA16(cur1.ka0, q0[1], sA1); sB0 = MFMA16(cur0.kb0, q0[0], sB0); sB1 = MFMA16(cur1.kb0, q0[1], sB1);
;             sA0 = MFMA16(cur0.ka1, q1[0], sA0); sA1 = MFMA16(cur1.ka1, q1[1], sA1); sB0 = MFMA16(cur0.kb1, q1[0], sB0); sB1 = MFMA16(cur1.kb1, q1[1], sB1);
;             LDS_FENCE();
;             { bf16_t* d = Vs + (lane >> 3) * 68 + 8 * (lane & 7);
;               *(u32x2*)d = (u32x2){cur0.v0.x, cur0.v0.y}; *(u32x2*)(d + 4) = (u32x2){cur0.v0.z, cur0.v0.w};
;               *(u32x2*)(d + 8 * 68) = (u32x2){cur0.v1.x, cur0.v1.y}; *(u32x2*)(d + 8 * 68 + 4) = (u32x2){cur0.v1.z, cur0.v1.w};
;               *(u32x2*)(d + 16 * 68) = (u32x2){cur0.v2.x, cur0.v2.y}; *(u32x2*)(d + 16 * 68 + 4) = (u32x2){cur0.v2.z, cur0.v2.w};
;               *(u32x2*)(d + 24 * 68) = (u32x2){cur0.v3.x, cur0.v3.y}; *(u32x2*)(d + 24 * 68 + 4) = (u32x2){cur0.v3.z, cur0.v3.w};
;               d = Vs1 + (lane >> 3) * 68 + 8 * (lane & 7);
;               *(u32x2*)d = (u32x2){cur1.v0.x, cur1.v0.y}; *(u32x2*)(d + 4) = (u32x2){cur1.v0.z, cur1.v0.w};
;               *(u32x2*)(d + 8 * 68) = (u32x2){cur1.v1.x, cur1.v1.y}; *(u32x2*)(d + 8 * 68 + 4) = (u32x2){cur1.v1.z, cur1.v1.w};
;               *(u32x2*)(d + 16 * 68) = (u32x2){cur1.v2.x, cur1.v2.y}; *(u32x2*)(d + 16 * 68 + 4) = (u32x2){cur1.v2.z, cur1.v2.w};
;               *(u32x2*)(d + 24 * 68) = (u32x2){cur1.v3.x, cur1.v3.y}; *(u32x2*)(d + 24 * 68 + 4) = (u32x2){cur1.v3.z, cur1.v3.w}; }
;             const bf16x8 P0_ = attn_softmax_step(sA0, sB0, cb, cq, ncls, g, m[0], lsum[0], O[0]);
;             const bf16x8 P1_ = attn_softmax_step(sA1, sB1, cb, cq, ncls, g, m[1], lsum[1], O[1]);
	v_mfma_f32_16x16x32_bf16 v[120:123], v[120:123], v[44:47], v[124:127]
	global_load_dwordx4 v[48:51], v[52:53], off
	s_nop 0
	global_load_dwordx4 v[52:55], v[52:53], off offset:64
	s_nop 0
	global_load_dwordx4 v[64:67], v[68:69], off
	s_nop 0
	global_load_dwordx4 v[68:71], v[68:69], off offset:64
	v_add_u32_e32 v124, 0x880, v222
	global_load_dwordx4 v[72:75], v[72:73], off
	v_mfma_f32_16x16x32_bf16 v[140:143], v[140:143], v[40:43], 0
	global_load_dwordx4 v[76:79], v[76:77], off
	v_mov_b32_e32 v226, v183
	global_load_dwordx4 v[80:83], v[80:81], off
	v_mfma_f32_16x16x32_bf16 v[136:139], v[136:139], v[44:47], v[140:143]
	global_load_dwordx4 v[84:87], v[84:85], off
	s_waitcnt lgkmcnt(0)
	s_waitcnt vmcnt(27)
	ds_write2_b64 v222, v[132:133], v[134:135] offset1:1
	s_waitcnt vmcnt(26)
	ds_write2_b64 v222, v[128:129], v[130:131] offset0:136 offset1:137
	s_waitcnt vmcnt(25)
	ds_write2_b64 v124, v[116:117], v[118:119] offset1:1
	v_add_u32_e32 v116, 0xcc0, v222
	s_waitcnt vmcnt(24)
	ds_write2_b64 v116, v[112:113], v[114:115] offset1:1
	v_add_u32_e32 v112, 0x8800, v222
	s_waitcnt vmcnt(19)
	ds_write2_b64 v112, v[156:157], v[158:159] offset1:1
	v_add_u32_e32 v112, 0x8c40, v222
	s_waitcnt vmcnt(18)
	ds_write2_b64 v112, v[148:149], v[150:151] offset1:1
	v_add_u32_e32 v112, 0x9080, v222
	s_waitcnt vmcnt(17)
	ds_write2_b64 v112, v[152:153], v[154:155] offset1:1
	v_add_u32_e32 v112, 0x94c0, v222
	s_waitcnt vmcnt(16)
	ds_write2_b64 v112, v[144:145], v[146:147] offset1:1
	v_add_u32_e32 v112, s15, v224
	v_subrev_u32_e32 v113, 64, v112
	v_add_u32_e32 v114, s15, v225
	v_cmp_gt_u32_e32 vcc, s91, v113
	v_cmp_gt_u32_e64 s[36:37], s78, v114
	v_subrev_u32_e32 v115, 63, v112
	s_and_b64 vcc, vcc, s[36:37]
	v_cmp_gt_u32_e64 s[36:37], s91, v115
	v_add_u32_e32 v115, 1, v114
	v_cmp_gt_u32_e64 s[38:39], s78, v115
	v_subrev_u32_e32 v116, 62, v112
	s_and_b64 s[36:37], s[36:37], s[38:39]
	v_cmp_gt_u32_e64 s[38:39], s91, v116
	v_add_u32_e32 v116, 2, v114
	v_cmp_gt_u32_e64 s[40:41], s78, v116
	v_subrev_u32_e32 v116, 61, v112
	s_and_b64 s[38:39], s[38:39], s[40:41]
	v_cmp_gt_u32_e64 s[40:41], s91, v116
	v_add_u32_e32 v116, 3, v114
	v_cmp_gt_u32_e64 s[42:43], s78, v116
	v_subrev_u32_e32 v116, 60, v112
	s_and_b64 s[40:41], s[40:41], s[42:43]
	v_cmp_gt_u32_e64 s[42:43], s91, v116
	v_add_u32_e32 v116, 4, v114
	v_cmp_gt_u32_e64 s[44:45], s78, v116
	v_subrev_u32_e32 v116, 59, v112
	s_and_b64 s[42:43], s[42:43], s[44:45]
	v_cmp_gt_u32_e64 s[44:45], s91, v116
	v_add_u32_e32 v116, 5, v114
	v_cmp_gt_u32_e64 s[46:47], s78, v116
	v_subrev_u32_e32 v116, 58, v112
	s_and_b64 s[44:45], s[44:45], s[46:47]
	v_cmp_gt_u32_e64 s[46:47], s91, v116
	v_add_u32_e32 v116, 6, v114
	v_cmp_gt_u32_e64 s[48:49], s78, v116
	v_subrev_u32_e32 v112, 57, v112
	s_and_b64 s[46:47], s[46:47], s[48:49]
	v_cmp_gt_u32_e64 s[48:49], s91, v112
	v_add_u32_e32 v112, 7, v114
	v_cndmask_b32_e32 v113, v205, v136, vcc
	v_cndmask_b32_e64 v115, v205, v137, s[36:37]
	v_cmp_gt_u32_e64 s[50:51], s78, v112
	v_cndmask_b32_e64 v117, v205, v138, s[38:39]
	v_cndmask_b32_e64 v119, v205, v139, s[40:41]
	s_and_b64 s[48:49], s[48:49], s[50:51]
	v_cndmask_b32_e64 v125, v205, v122, s[46:47]
	v_cndmask_b32_e64 v112, v205, v123, s[48:49]
	v_max_f32_e32 v114, v113, v115
	v_cndmask_b32_e64 v124, v205, v120, s[42:43]
	v_max_f32_e32 v116, v117, v119
	v_cndmask_b32_e64 v121, v205, v121, s[44:45]
	v_max_f32_e32 v118, v125, v112
	v_max3_f32 v118, v124, v121, v118
	v_max3_f32 v114, v114, v116, v118
	v_mov_b32_e32 v116, v114
	s_nop 1
	v_permlane16_swap_b32_e32 v114, v116
	v_mfma_f32_16x16x32_bf16 v[172:175], v[172:175], v[0:3], 0
	v_max_f32_e32 v114, v114, v116
	v_mov_b32_e32 v116, v114
	s_nop 1
	v_permlane32_swap_b32_e32 v114, v116
	v_mfma_f32_16x16x32_bf16 v[164:167], v[164:167], v[0:3], 0
	v_max3_f32 v183, v226, v114, v116
	v_sub_f32_e32 v114, v226, v183
	v_sub_f32_e32 v113, v113, v183
	v_mfma_f32_16x16x32_bf16 v[140:143], v[168:171], v[4:7], v[172:175]
	v_exp_f32_e32 v116, v113
	v_sub_f32_e32 v113, v115, v183
	v_exp_f32_e32 v132, v114
	v_mfma_f32_16x16x32_bf16 v[160:163], v[160:163], v[4:7], v[164:167]
	v_exp_f32_e32 v118, v113
	v_sub_f32_e32 v113, v117, v183
	v_exp_f32_e32 v120, v113
	v_sub_f32_e32 v113, v119, v183
	v_exp_f32_e32 v122, v113
	v_sub_f32_e32 v113, v124, v183
	v_cndmask_b32_e32 v117, v205, v140, vcc
	v_cndmask_b32_e64 v119, v205, v141, s[36:37]
	v_exp_f32_e32 v124, v113
	v_sub_f32_e32 v113, v121, v183
	v_pk_mul_f32 v[30:31], v[30:31], v[132:133] op_sel_hi:[1,0]
	v_pk_mul_f32 v[28:29], v[28:29], v[132:133] op_sel_hi:[1,0]
	v_pk_mul_f32 v[26:27], v[26:27], v[132:133] op_sel_hi:[1,0]
	v_pk_mul_f32 v[24:25], v[24:25], v[132:133] op_sel_hi:[1,0]
	v_pk_mul_f32 v[34:35], v[34:35], v[132:133] op_sel_hi:[1,0]
	v_pk_mul_f32 v[32:33], v[32:33], v[132:133] op_sel_hi:[1,0]
	v_pk_mul_f32 v[38:39], v[38:39], v[132:133] op_sel_hi:[1,0]
	v_pk_mul_f32 v[36:37], v[36:37], v[132:133] op_sel_hi:[1,0]
	v_cndmask_b32_e64 v121, v205, v142, s[38:39]
	v_cndmask_b32_e64 v123, v205, v143, s[40:41]
	v_cndmask_b32_e64 v129, v205, v162, s[46:47]
	v_cndmask_b32_e64 v131, v205, v163, s[48:49]
	v_max_f32_e32 v133, v117, v119
	v_max_f32_e32 v134, v121, v123
	v_exp_f32_e32 v126, v113
	v_sub_f32_e32 v113, v125, v183
	v_cndmask_b32_e64 v125, v205, v160, s[42:43]
	v_cndmask_b32_e64 v127, v205, v161, s[44:45]
	v_max_f32_e32 v135, v129, v131
	v_max3_f32 v135, v125, v127, v135
	v_max3_f32 v133, v133, v134, v135
	v_mov_b32_e32 v134, v133
	s_nop 1
	v_permlane16_swap_b32_e32 v133, v134
	v_max_f32_e32 v133, v133, v134
	v_mov_b32_e32 v134, v133
	s_nop 1
	v_permlane32_swap_b32_e32 v133, v134
	v_mov_b32_e32 v135, v177
	v_max3_f32 v177, v135, v133, v134
	v_sub_f32_e32 v117, v117, v177
	v_exp_f32_e32 v117, v117
	v_sub_f32_e32 v119, v119, v177
	v_exp_f32_e32 v119, v119
	v_sub_f32_e32 v121, v121, v177
	v_sub_f32_e32 v133, v135, v177
	v_exp_f32_e32 v121, v121
	v_sub_f32_e32 v123, v123, v177
	v_exp_f32_e32 v123, v123
	v_sub_f32_e32 v125, v125, v177
	v_sub_f32_e32 v127, v127, v177
	v_exp_f32_e32 v133, v133
	v_exp_f32_e32 v125, v125
	v_exp_f32_e32 v127, v127
	v_pk_add_f32 v[134:135], v[116:117], 0 op_sel_hi:[1,0]
	v_sub_f32_e32 v112, v112, v183
	v_pk_add_f32 v[134:135], v[118:119], v[134:135]
	v_exp_f32_e32 v128, v113
	v_pk_add_f32 v[134:135], v[120:121], v[134:135]
	v_exp_f32_e32 v130, v112
	v_cvt_pk_bf16_f32 v112, v116, v118
	v_pk_add_f32 v[134:135], v[122:123], v[134:135]
	v_mov_b32_e32 v116, v133
	s_waitcnt lgkmcnt(0)
; #define LDS_FENCE() asm volatile("s_waitcnt lgkmcnt(0)" ::: "memory")
; #define MFMA16(a, b, c) __builtin_amdgcn_mfma_f32_16x16x32_bf16((a), (b), (c), 0, 0, 0)
; template <int NROWS>
; __device__ __forceinline__ void attn_stage(const bf16_t* __restrict__ ka, const bf16_t* __restrict__ va, bf16_t* Kt, bf16_t* Vt, int c0, int ncls, int rd, int dsh, int tid) {
;     ...
;     for (int u = 0; u < IT; ++u) { const int idx = min(tid + u * NTHR, NROWS * 16 - 1);
;         const int i = idx >> 4, ch = idx & 15, isv = ch >> 3, c8 = ch & 7; const int c = min(max(c0 + i, 0), ncls - 1);
;         v[u] = *(const u32x4*)((isv ? va : ka) + (size_t)(rd + (c << dsh)) * 64 + 8 * c8); }
; __device__ __forceinline__ void attn_item(const bf16_t* __restrict__ Z, const bf16_t* __restrict__ KA, const bf16_t* __restrict__ VA, bf16_t* __restrict__ MIX, int S, int it) {
;     ...
;             LDS_FENCE();
; #pragma unroll
;             for (int nbk = 0; nbk < 4; ++nbk) { O[0][nbk] = MFMA16(gather8(Vs + (8 * g) * 68 + 16 * nbk, 68, qi), P0_, O[0][nbk]); O[1][nbk] = MFMA16(gather8(Vs1 + (8 * g) * 68 + 16 * nbk, 68, qi), P1_, O[1][nbk]); }
;             cur0 = nxt0; cur1 = nxt1;
;         }
;         LDS_FENCE();
;     }
;     __syncthreads();
;     attn_stage<400>(ka, va, Kt, Vt, P0 - 64, S, 0, 0, tid);
	v_cvt_pk_bf16_f32 v113, v120, v122
	v_cvt_pk_bf16_f32 v114, v124, v126
	v_pk_add_f32 v[134:135], v[124:125], v[134:135]
	v_pk_mul_f32 v[18:19], v[18:19], v[116:117] op_sel_hi:[1,0]
	v_pk_mul_f32 v[16:17], v[16:17], v[116:117] op_sel_hi:[1,0]
	v_pk_mul_f32 v[10:11], v[10:11], v[116:117] op_sel_hi:[1,0]
	v_pk_mul_f32 v[8:9], v[8:9], v[116:117] op_sel_hi:[1,0]
	v_pk_mul_f32 v[22:23], v[22:23], v[116:117] op_sel_hi:[1,0]
	v_pk_mul_f32 v[20:21], v[20:21], v[116:117] op_sel_hi:[1,0]
	v_pk_mul_f32 v[14:15], v[14:15], v[116:117] op_sel_hi:[1,0]
	v_pk_mul_f32 v[12:13], v[12:13], v[116:117] op_sel_hi:[1,0]
	v_cvt_pk_bf16_f32 v116, v117, v119
	v_cvt_pk_bf16_f32 v117, v121, v123
	v_cvt_pk_bf16_f32 v118, v125, v127
	ds_read_b64_tr_b16 v[122:123], v223 offset:544
	ds_read_b64_tr_b16 v[120:121], v223
	ds_read_b64_tr_b16 v[124:125], v223 offset:32
	v_cvt_pk_bf16_f32 v115, v128, v130
	v_sub_f32_e32 v129, v129, v177
	v_sub_f32_e32 v131, v131, v177
	v_exp_f32_e32 v129, v129
	v_exp_f32_e32 v131, v131
	s_waitcnt lgkmcnt(1)
	v_mfma_f32_16x16x32_bf16 v[28:31], v[120:123], v[112:115], v[28:31]
	ds_read_b64_tr_b16 v[120:121], v223 offset:34816
	ds_read_b64_tr_b16 v[122:123], v223 offset:35360
	v_pk_add_f32 v[134:135], v[126:127], v[134:135]
	v_cvt_pk_bf16_f32 v119, v129, v131
	ds_read_b64_tr_b16 v[126:127], v223 offset:576
	s_waitcnt lgkmcnt(0)
	v_mfma_f32_16x16x32_bf16 v[24:27], v[124:127], v[112:115], v[24:27]
	v_add_f32_e64 v134, v128, v134
	v_add_f32_e64 v135, v129, v135
	s_add_i32 s15, s15, 32
	v_pk_add_f32 v[134:135], v[130:131], v[134:135]
	v_mfma_f32_16x16x32_bf16 v[16:19], v[120:123], v[116:119], v[16:19]
	ds_read_b64_tr_b16 v[120:121], v223 offset:34848
	ds_read_b64_tr_b16 v[122:123], v223 offset:35392
	v_pk_fma_f32 v[184:185], v[184:185], v[132:133], v[134:135]
	s_add_i32 s18, s18, 1
	s_waitcnt lgkmcnt(0)
	v_mfma_f32_16x16x32_bf16 v[8:11], v[120:123], v[116:119], v[8:11]
	ds_read_b64_tr_b16 v[120:121], v223 offset:64
	ds_read_b64_tr_b16 v[122:123], v223 offset:608
	s_waitcnt vmcnt(10)
	v_mov_b64_e32 v[130:131], v[102:103]
	v_mov_b64_e32 v[134:135], v[98:99]
	s_waitcnt lgkmcnt(0)
	v_mfma_f32_16x16x32_bf16 v[32:35], v[120:123], v[112:115], v[32:35]
	ds_read_b64_tr_b16 v[120:121], v223 offset:34880
	ds_read_b64_tr_b16 v[122:123], v223 offset:35424
	v_mov_b64_e32 v[126:127], v[90:91]
	v_mov_b64_e32 v[138:139], v[62:63]
	s_waitcnt lgkmcnt(0)
	v_mfma_f32_16x16x32_bf16 v[20:23], v[120:123], v[116:119], v[20:23]
	ds_read_b64_tr_b16 v[120:121], v223 offset:96
	ds_read_b64_tr_b16 v[122:123], v223 offset:640
	v_mov_b64_e32 v[142:143], v[58:59]
	s_waitcnt vmcnt(0)
	v_mov_b64_e32 v[146:147], v[86:87]
	s_waitcnt lgkmcnt(0)
	v_mfma_f32_16x16x32_bf16 v[36:39], v[120:123], v[112:115], v[36:39]
	ds_read_b64_tr_b16 v[112:113], v223 offset:34912
	ds_read_b64_tr_b16 v[114:115], v223 offset:35456
	v_mov_b64_e32 v[122:123], v[94:95]
	v_mov_b64_e32 v[154:155], v[82:83]
	s_waitcnt lgkmcnt(0)
	v_mfma_f32_16x16x32_bf16 v[12:15], v[112:115], v[116:119], v[12:15]
	v_mov_b64_e32 v[114:115], v[110:111]
	v_mov_b64_e32 v[118:119], v[106:107]
	v_mov_b64_e32 v[150:151], v[78:79]
	v_mov_b64_e32 v[158:159], v[74:75]
	v_mov_b64_e32 v[162:163], v[70:71]
	v_mov_b64_e32 v[166:167], v[66:67]
	v_mov_b64_e32 v[170:171], v[54:55]
	v_mov_b64_e32 v[174:175], v[50:51]
	s_cmpk_eq_i32 s15, 0xa0
	v_mov_b64_e32 v[112:113], v[108:109]
	v_mov_b64_e32 v[116:117], v[104:105]
	v_mov_b64_e32 v[128:129], v[100:101]
	v_mov_b64_e32 v[132:133], v[96:97]
	v_mov_b64_e32 v[120:121], v[92:93]
	v_mov_b64_e32 v[124:125], v[88:89]
	v_mov_b64_e32 v[136:137], v[60:61]
	v_mov_b64_e32 v[140:141], v[56:57]
	v_mov_b64_e32 v[144:145], v[84:85]
	v_mov_b64_e32 v[152:153], v[80:81]
	v_mov_b64_e32 v[148:149], v[76:77]
	v_mov_b64_e32 v[156:157], v[72:73]
	v_mov_b64_e32 v[160:161], v[68:69]
	v_mov_b64_e32 v[164:165], v[64:65]
	v_mov_b64_e32 v[168:169], v[52:53]
	v_mov_b64_e32 v[172:173], v[48:49]
	s_cbranch_scc0 .LBB0_401
	v_min_i32_e32 v52, 0x18ff, v187
	s_sub_i32 s3, s12, 64
	v_ashrrev_i32_e32 v124, 4, v52
	v_add_u32_e32 v48, s3, v124
	v_max_i32_e32 v48, 0, v48
	v_and_b32_e32 v125, 8, v52
	v_min_u32_e32 v178, s90, v48
	v_mov_b32_e32 v99, s95
	v_mov_b32_e32 v100, s7
	v_cmp_eq_u32_e32 vcc, 0, v125
	v_mov_b32_e32 v122, s94
	v_mov_b32_e32 v123, s6
	v_cndmask_b32_e32 v49, v99, v100, vcc
	v_cndmask_b32_e32 v48, v122, v123, vcc
	v_lshlrev_b64 v[50:51], 7, v[178:179]
	v_min_i32_e32 v56, 0x16ff, v187
	v_lshl_add_u64 v[48:49], v[48:49], 0, v[50:51]
	v_lshlrev_b32_e32 v50, 4, v52
	v_add_u32_e32 v52, 0x200, v56
	v_ashrrev_i32_e32 v126, 4, v52
	v_add_u32_e32 v52, s3, v126
	v_max_i32_e32 v52, 0, v52
	v_and_b32_e32 v127, 8, v56
	v_min_u32_e32 v52, s90, v52
	v_cmp_eq_u32_e64 s[36:37], 0, v127
	v_mov_b32_e32 v53, v179
	v_lshlrev_b64 v[52:53], 7, v[52:53]
	v_cndmask_b32_e64 v55, v99, v100, s[36:37]
	v_cndmask_b32_e64 v54, v122, v123, s[36:37]
	v_lshl_add_u64 v[52:53], v[54:55], 0, v[52:53]
	v_lshlrev_b32_e32 v54, 4, v56
	v_and_b32_e32 v56, 0x70, v54
	v_mov_b32_e32 v57, v179
	v_lshl_add_u64 v[52:53], v[52:53], 0, v[56:57]
	v_min_i32_e32 v57, 0x14ff, v187
	v_add_u32_e32 v58, 0x400, v57
	v_ashrrev_i32_e32 v128, 4, v58
	v_add_u32_e32 v58, s3, v128
	v_max_i32_e32 v58, 0, v58
	v_and_b32_e32 v129, 8, v57
	v_min_u32_e32 v58, s90, v58
	v_cmp_eq_u32_e64 s[38:39], 0, v129
	v_mov_b32_e32 v59, v179
	v_lshlrev_b32_e32 v57, 4, v57
	v_cndmask_b32_e64 v61, v99, v100, s[38:39]
	v_cndmask_b32_e64 v60, v122, v123, s[38:39]
	v_lshlrev_b64 v[58:59], 7, v[58:59]
	v_and_b32_e32 v102, 0x70, v57
	v_min_i32_e32 v57, 0x12ff, v187
	v_lshl_add_u64 v[58:59], v[60:61], 0, v[58:59]
	v_mov_b32_e32 v103, v179
	v_add_u32_e32 v62, 0x600, v57
	v_lshl_add_u64 v[58:59], v[58:59], 0, v[102:103]
; template <int NROWS>
; __device__ __forceinline__ void attn_stage(const bf16_t* __restrict__ ka, const bf16_t* __restrict__ va, bf16_t* Kt, bf16_t* Vt, int c0, int ncls, int rd, int dsh, int tid) {
;     ...
;     for (int u = 0; u < IT; ++u) { const int idx = min(tid + u * NTHR, NROWS * 16 - 1);
;         const int i = idx >> 4, ch = idx & 15, isv = ch >> 3, c8 = ch & 7; const int c = min(max(c0 + i, 0), ncls - 1);
;         v[u] = *(const u32x4*)((isv ? va : ka) + (size_t)(rd + (c << dsh)) * 64 + 8 * c8); }
; #pragma unroll
;     for (int u = 0; u < IT; ++u) { const int idx = min(tid + u * NTHR, NROWS * 16 - 1);
;         const int i = idx >> 4, ch = idx & 15, isv = ch >> 3, c8 = ch & 7;
;         bf16_t* d = isv ? (Vt + i * 68 + 8 * c8) : (Kt + i * 72 + 8 * c8);
;         *(u32x2*)d = (u32x2){v[u].x, v[u].y}; *(u32x2*)(d + 4) = (u32x2){v[u].z, v[u].w}; }
	v_ashrrev_i32_e32 v103, 4, v62
	v_add_u32_e32 v62, s3, v103
	v_max_i32_e32 v62, 0, v62
	v_and_b32_e32 v130, 8, v57
	v_min_u32_e32 v62, s90, v62
	v_cmp_eq_u32_e64 s[40:41], 0, v130
	v_mov_b32_e32 v63, v179
	v_lshlrev_b32_e32 v57, 4, v57
	v_cndmask_b32_e64 v65, v99, v100, s[40:41]
	v_cndmask_b32_e64 v64, v122, v123, s[40:41]
	v_lshlrev_b64 v[62:63], 7, v[62:63]
	v_and_b32_e32 v104, 0x70, v57
	v_min_i32_e32 v57, 0x10ff, v187
	v_lshl_add_u64 v[62:63], v[64:65], 0, v[62:63]
	v_mov_b32_e32 v105, v179
	v_add_u32_e32 v66, 0x800, v57
	v_lshl_add_u64 v[62:63], v[62:63], 0, v[104:105]
	v_ashrrev_i32_e32 v105, 4, v66
	v_add_u32_e32 v66, s3, v105
	v_max_i32_e32 v66, 0, v66
	v_and_b32_e32 v131, 8, v57
	v_min_u32_e32 v66, s90, v66
	v_cmp_eq_u32_e64 s[42:43], 0, v131
	v_mov_b32_e32 v67, v179
	v_lshlrev_b32_e32 v57, 4, v57
	v_cndmask_b32_e64 v69, v99, v100, s[42:43]
	v_cndmask_b32_e64 v68, v122, v123, s[42:43]
	v_lshlrev_b64 v[66:67], 7, v[66:67]
	v_and_b32_e32 v106, 0x70, v57
	v_min_i32_e32 v57, 0xeff, v187
	v_lshl_add_u64 v[66:67], v[68:69], 0, v[66:67]
	v_mov_b32_e32 v107, v179
	v_add_u32_e32 v70, 0xa00, v57
	v_lshl_add_u64 v[66:67], v[66:67], 0, v[106:107]
	v_ashrrev_i32_e32 v107, 4, v70
	v_add_u32_e32 v70, s3, v107
	v_max_i32_e32 v70, 0, v70
	v_and_b32_e32 v132, 8, v57
	v_min_u32_e32 v70, s90, v70
	v_cmp_eq_u32_e64 s[44:45], 0, v132
	v_mov_b32_e32 v71, v179
	v_lshlrev_b32_e32 v57, 4, v57
	v_cndmask_b32_e64 v73, v99, v100, s[44:45]
	v_cndmask_b32_e64 v72, v122, v123, s[44:45]
	v_lshlrev_b64 v[70:71], 7, v[70:71]
	v_and_b32_e32 v108, 0x70, v57
	v_min_i32_e32 v57, 0xcff, v187
	v_lshl_add_u64 v[70:71], v[72:73], 0, v[70:71]
	v_mov_b32_e32 v109, v179
	v_add_u32_e32 v74, 0xc00, v57
	v_lshl_add_u64 v[70:71], v[70:71], 0, v[108:109]
	v_ashrrev_i32_e32 v109, 4, v74
	v_add_u32_e32 v74, s3, v109
	v_and_b32_e32 v178, 0x70, v50
	v_max_i32_e32 v74, 0, v74
	v_and_b32_e32 v133, 8, v57
	v_lshl_add_u64 v[48:49], v[48:49], 0, v[178:179]
	v_min_u32_e32 v74, s90, v74
	v_cmp_eq_u32_e64 s[46:47], 0, v133
	v_mov_b32_e32 v75, v179
	v_lshlrev_b32_e32 v57, 4, v57
	s_waitcnt lgkmcnt(0)
	s_barrier
	global_load_dwordx4 v[48:51], v[48:49], off
	v_cndmask_b32_e64 v77, v99, v100, s[46:47]
	v_cndmask_b32_e64 v76, v122, v123, s[46:47]
	v_lshlrev_b64 v[74:75], 7, v[74:75]
	v_and_b32_e32 v110, 0x70, v57
	v_min_i32_e32 v57, 0xaff, v187
	v_lshl_add_u64 v[74:75], v[76:77], 0, v[74:75]
	v_mov_b32_e32 v111, v179
	v_add_u32_e32 v78, 0xe00, v57
	v_lshl_add_u64 v[74:75], v[74:75], 0, v[110:111]
	v_ashrrev_i32_e32 v111, 4, v78
	global_load_dwordx4 v[52:55], v[52:53], off
	v_add_u32_e32 v78, s3, v111
	v_max_i32_e32 v78, 0, v78
	v_and_b32_e32 v134, 8, v57
	v_min_u32_e32 v78, s90, v78
	v_cmp_eq_u32_e64 s[48:49], 0, v134
	v_mov_b32_e32 v79, v179
	v_lshlrev_b32_e32 v57, 4, v57
	global_load_dwordx4 v[58:61], v[58:59], off
	v_cndmask_b32_e64 v81, v99, v100, s[48:49]
	v_cndmask_b32_e64 v80, v122, v123, s[48:49]
	v_lshlrev_b64 v[78:79], 7, v[78:79]
	v_and_b32_e32 v112, 0x70, v57
	v_min_i32_e32 v57, 0x8ff, v187
	v_lshl_add_u64 v[78:79], v[80:81], 0, v[78:79]
	v_mov_b32_e32 v113, v179
	v_add_u32_e32 v82, 0x1000, v57
	v_lshl_add_u64 v[78:79], v[78:79], 0, v[112:113]
	v_ashrrev_i32_e32 v113, 4, v82
	global_load_dwordx4 v[62:65], v[62:63], off
	v_add_u32_e32 v82, s3, v113
	v_max_i32_e32 v82, 0, v82
	v_and_b32_e32 v135, 8, v57
	v_min_u32_e32 v82, s90, v82
	v_cmp_eq_u32_e64 s[50:51], 0, v135
	v_mov_b32_e32 v83, v179
	v_lshlrev_b32_e32 v57, 4, v57
	global_load_dwordx4 v[66:69], v[66:67], off
	v_cndmask_b32_e64 v85, v99, v100, s[50:51]
	v_cndmask_b32_e64 v84, v122, v123, s[50:51]
	v_lshlrev_b64 v[82:83], 7, v[82:83]
	v_and_b32_e32 v114, 0x70, v57
	v_min_i32_e32 v57, 0x6ff, v187
	v_lshl_add_u64 v[82:83], v[84:85], 0, v[82:83]
	v_mov_b32_e32 v115, v179
	v_add_u32_e32 v86, 0x1200, v57
	v_lshl_add_u64 v[82:83], v[82:83], 0, v[114:115]
	v_ashrrev_i32_e32 v115, 4, v86
	global_load_dwordx4 v[70:73], v[70:71], off
	v_add_u32_e32 v86, s3, v115
	v_max_i32_e32 v86, 0, v86
	v_and_b32_e32 v136, 8, v57
	v_min_u32_e32 v86, s90, v86
	v_cmp_eq_u32_e64 s[52:53], 0, v136
	v_mov_b32_e32 v87, v179
	v_lshlrev_b32_e32 v57, 4, v57
	global_load_dwordx4 v[74:77], v[74:75], off
	v_cndmask_b32_e64 v89, v99, v100, s[52:53]
	v_cndmask_b32_e64 v88, v122, v123, s[52:53]
	v_lshlrev_b64 v[86:87], 7, v[86:87]
	v_and_b32_e32 v116, 0x70, v57
	v_min_i32_e32 v57, 0x4ff, v187
	v_lshl_add_u64 v[86:87], v[88:89], 0, v[86:87]
	v_mov_b32_e32 v117, v179
	v_add_u32_e32 v90, 0x1400, v57
	v_lshl_add_u64 v[86:87], v[86:87], 0, v[116:117]
	v_ashrrev_i32_e32 v117, 4, v90
	global_load_dwordx4 v[78:81], v[78:79], off
	v_add_u32_e32 v90, s3, v117
	v_max_i32_e32 v90, 0, v90
	v_and_b32_e32 v137, 8, v57
	v_min_u32_e32 v90, s90, v90
	v_cmp_eq_u32_e64 s[54:55], 0, v137
	v_mov_b32_e32 v91, v179
	v_lshlrev_b32_e32 v57, 4, v57
	global_load_dwordx4 v[82:85], v[82:83], off
	v_cndmask_b32_e64 v93, v99, v100, s[54:55]
	v_cndmask_b32_e64 v92, v122, v123, s[54:55]
	v_lshlrev_b64 v[90:91], 7, v[90:91]
	v_and_b32_e32 v118, 0x70, v57
	v_min_i32_e32 v57, 0x2ff, v187
	v_lshl_add_u64 v[90:91], v[92:93], 0, v[90:91]
	v_mov_b32_e32 v119, v179
	v_add_u32_e32 v94, 0x1600, v57
	v_lshl_add_u64 v[90:91], v[90:91], 0, v[118:119]
	v_ashrrev_i32_e32 v119, 4, v94
	global_load_dwordx4 v[86:89], v[86:87], off
	v_add_u32_e32 v94, s3, v119
	v_max_i32_e32 v94, 0, v94
	v_and_b32_e32 v138, 8, v57
	v_min_u32_e32 v94, s90, v94
	v_cmp_eq_u32_e64 s[56:57], 0, v138
	v_mov_b32_e32 v95, v179
	global_load_dwordx4 v[90:93], v[90:91], off
	v_cndmask_b32_e64 v97, v99, v100, s[56:57]
	v_cndmask_b32_e64 v96, v122, v123, s[56:57]
	v_lshlrev_b64 v[94:95], 7, v[94:95]
	v_lshlrev_b32_e32 v57, 4, v57
	v_lshl_add_u64 v[94:95], v[96:97], 0, v[94:95]
	v_and_b32_e32 v120, 0x70, v57
	v_mov_b32_e32 v121, v179
	v_min_i32_e32 v57, 0xff, v187
	v_lshl_add_u64 v[94:95], v[94:95], 0, v[120:121]
	v_add_u32_e32 v98, 0x1800, v57
	global_load_dwordx4 v[94:97], v[94:95], off
	v_ashrrev_i32_e32 v121, 4, v98
	v_add_u32_e32 v98, s3, v121
	v_and_b32_e32 v139, 8, v57
	v_max_i32_e32 v98, 0, v98
	v_cmp_eq_u32_e64 s[58:59], 0, v139
	v_min_u32_e32 v98, s90, v98
	v_lshlrev_b32_e32 v57, 4, v57
	v_cndmask_b32_e64 v101, v99, v100, s[58:59]
	v_mov_b32_e32 v99, v179
	v_cndmask_b32_e64 v100, v122, v123, s[58:59]
	v_lshlrev_b64 v[98:99], 7, v[98:99]
	v_lshl_add_u64 v[98:99], v[100:101], 0, v[98:99]
	v_and_b32_e32 v122, 0x70, v57
	v_mov_b32_e32 v123, v179
	v_lshl_add_u64 v[98:99], v[98:99], 0, v[122:123]
	global_load_dwordx4 v[98:101], v[98:99], off
	v_readlane_b32 s15, v255, 0
	v_sub_u32_e32 v57, 0x90, v125
	v_mul_lo_u32 v57, v57, v124
	v_mov_b32_e32 v123, s15
	v_cndmask_b32_e64 v125, v123, 0, vcc
	v_add3_u32 v57, v125, v57, v178
	s_waitcnt vmcnt(12)
; template <int NROWS>
; __device__ __forceinline__ void attn_stage(const bf16_t* __restrict__ ka, const bf16_t* __restrict__ va, bf16_t* Kt, bf16_t* Vt, int c0, int ncls, int rd, int dsh, int tid) {
;     ...
;     for (int u = 0; u < IT; ++u) { const int idx = min(tid + u * NTHR, NROWS * 16 - 1);
;         const int i = idx >> 4, ch = idx & 15, isv = ch >> 3, c8 = ch & 7;
;         bf16_t* d = isv ? (Vt + i * 68 + 8 * c8) : (Kt + i * 72 + 8 * c8);
;         *(u32x2*)d = (u32x2){v[u].x, v[u].y}; *(u32x2*)(d + 4) = (u32x2){v[u].z, v[u].w}; }
; __device__ __forceinline__ void attn_item(const bf16_t* __restrict__ Z, const bf16_t* __restrict__ KA, const bf16_t* __restrict__ VA, bf16_t* __restrict__ MIX, int S, int it) {
;     ...
; #pragma unroll 1
;     for (int i2 = 0; i2 < 12; ++i2) {
;         attn_lds_step(Kt, Vt, rt[0] + 32 * i2, q0[0], q1[0], P0 + rt[0] - 64 + 32 * i2, P0 + rt[0] + 16 * qi, S, qi, g, m[0], lsum[0], O[0]);
;         attn_lds_step(Kt, Vt, rt[1] + 32 * i2, q0[1], q1[1], P0 + rt[1] - 64 + 32 * i2, P0 + rt[1] + 16 * qi, S, qi, g, m[1], lsum[1], O[1]);
;     }
	ds_write2_b64 v57, v[48:49], v[50:51] offset1:1
	v_sub_u32_e32 v48, 0x90, v127
	v_cndmask_b32_e64 v49, v123, 0, s[36:37]
	v_mul_lo_u32 v48, v126, v48
	v_add3_u32 v48, v49, v48, v56
	s_waitcnt vmcnt(11)
	ds_write2_b64 v48, v[52:53], v[54:55] offset1:1
	v_sub_u32_e32 v48, 0x90, v129
	v_cndmask_b32_e64 v49, v123, 0, s[38:39]
	v_mul_lo_u32 v48, v128, v48
	v_add3_u32 v48, v49, v48, v102
	s_waitcnt vmcnt(10)
	ds_write2_b64 v48, v[58:59], v[60:61] offset1:1
	v_sub_u32_e32 v48, 0x90, v130
	v_cndmask_b32_e64 v49, v123, 0, s[40:41]
	v_mul_lo_u32 v48, v103, v48
	v_add3_u32 v48, v49, v48, v104
	s_waitcnt vmcnt(9)
	ds_write2_b64 v48, v[62:63], v[64:65] offset1:1
	v_sub_u32_e32 v48, 0x90, v131
	v_cndmask_b32_e64 v49, v123, 0, s[42:43]
	v_mul_lo_u32 v48, v105, v48
	v_add3_u32 v48, v49, v48, v106
	s_waitcnt vmcnt(8)
	ds_write2_b64 v48, v[66:67], v[68:69] offset1:1
	v_sub_u32_e32 v48, 0x90, v132
	v_cndmask_b32_e64 v49, v123, 0, s[44:45]
	v_mul_lo_u32 v48, v107, v48
	v_add3_u32 v48, v49, v48, v108
	s_waitcnt vmcnt(7)
	ds_write2_b64 v48, v[70:71], v[72:73] offset1:1
	v_sub_u32_e32 v48, 0x90, v133
	v_cndmask_b32_e64 v49, v123, 0, s[46:47]
	v_mul_lo_u32 v48, v109, v48
	v_add3_u32 v48, v49, v48, v110
	s_waitcnt vmcnt(6)
	ds_write2_b64 v48, v[74:75], v[76:77] offset1:1
	v_sub_u32_e32 v48, 0x90, v134
	v_cndmask_b32_e64 v49, v123, 0, s[48:49]
	v_mul_lo_u32 v48, v111, v48
	v_add3_u32 v48, v49, v48, v112
	s_waitcnt vmcnt(5)
	ds_write2_b64 v48, v[78:79], v[80:81] offset1:1
	v_sub_u32_e32 v48, 0x90, v135
	v_cndmask_b32_e64 v49, v123, 0, s[50:51]
	v_mul_lo_u32 v48, v113, v48
	v_add3_u32 v48, v49, v48, v114
	s_waitcnt vmcnt(4)
	ds_write2_b64 v48, v[82:83], v[84:85] offset1:1
	v_sub_u32_e32 v48, 0x90, v136
	v_cndmask_b32_e64 v49, v123, 0, s[52:53]
	v_mul_lo_u32 v48, v115, v48
	v_add3_u32 v48, v49, v48, v116
	s_waitcnt vmcnt(3)
	ds_write2_b64 v48, v[86:87], v[88:89] offset1:1
	v_sub_u32_e32 v48, 0x90, v137
	v_cndmask_b32_e64 v49, v123, 0, s[54:55]
	v_mul_lo_u32 v48, v117, v48
	v_add3_u32 v48, v49, v48, v118
	s_waitcnt vmcnt(2)
	ds_write2_b64 v48, v[90:91], v[92:93] offset1:1
	v_sub_u32_e32 v48, 0x90, v138
	v_cndmask_b32_e64 v49, v123, 0, s[56:57]
	v_mul_lo_u32 v48, v119, v48
	v_add3_u32 v48, v49, v48, v120
	v_cndmask_b32_e64 v49, v123, 0, s[58:59]
	s_movk_i32 s15, 0x220
	s_waitcnt vmcnt(1)
	ds_write2_b64 v48, v[94:95], v[96:97] offset1:1
	v_sub_u32_e32 v48, 0x90, v139
	v_mul_lo_u32 v48, v121, v48
	v_add3_u32 v48, v49, v48, v122
	v_lshrrev_b32_e32 v49, 2, v217
	v_mul_u32_u24_e32 v94, 0x440, v218
	v_mul_lo_u32 v50, v49, s15
	v_mul_u32_u24_e32 v51, 0x88, v211
	v_add3_u32 v50, v94, v50, v51
	v_lshlrev_b32_e32 v96, 3, v212
	v_add3_u32 v76, v50, v96, v219
	s_movk_i32 s15, 0x240
	v_add_u32_e32 v50, v211, v212
	v_mul_u32_u24_e32 v95, 0x480, v214
	v_mul_lo_u32 v49, v49, s15
	v_mul_u32_u24_e32 v51, 0x90, v50
	s_waitcnt vmcnt(0)
	ds_write2_b64 v48, v[98:99], v[100:101] offset1:1
	v_lshlrev_b32_e32 v48, 1, v215
	v_add3_u32 v49, v95, v49, v51
	v_lshlrev_b32_e32 v52, 4, v218
	s_movk_i32 s15, 0x120
	v_and_b32_e32 v53, 24, v48
	v_add3_u32 v48, v186, v216, v211
	v_add3_u32 v77, v49, v52, s15
	s_movk_i32 s15, 0x88
	v_add_u32_e32 v74, s12, v48
	v_mul_lo_u32 v48, v48, s15
	v_add3_u32 v78, v48, v96, v219
	v_add3_u32 v48, v53, v216, v50
	s_movk_i32 s15, 0x90
	s_mov_b32 s3, 0
	v_mad_i32_i24 v75, v215, -16, v186
	v_mad_u64_u32 v[54:55], s[18:19], v48, s15, v[52:53]
	s_waitcnt lgkmcnt(0)
	s_barrier
	s_waitcnt vmcnt(0)
	v_mov_b32_e32 v100, v8
	v_mov_b32_e32 v101, v9
	v_mov_b32_e32 v102, v10
	v_mov_b32_e32 v103, v11
	v_mov_b32_e32 v104, v12
	v_mov_b32_e32 v105, v13
	v_mov_b32_e32 v106, v14
	v_mov_b32_e32 v107, v15
	v_mov_b32_e32 v108, v16
	v_mov_b32_e32 v109, v17
	v_mov_b32_e32 v110, v18
	v_mov_b32_e32 v111, v19
	v_mov_b32_e32 v112, v20
	v_mov_b32_e32 v113, v21
	v_mov_b32_e32 v114, v22
	v_mov_b32_e32 v115, v23
	v_mov_b32_e32 v116, v24
	v_mov_b32_e32 v117, v25
	v_mov_b32_e32 v118, v26
	v_mov_b32_e32 v119, v27
	v_mov_b32_e32 v120, v28
	v_mov_b32_e32 v121, v29
	v_mov_b32_e32 v122, v30
	v_mov_b32_e32 v123, v31
	v_mov_b32_e32 v124, v32
	v_mov_b32_e32 v125, v33
	v_mov_b32_e32 v126, v34
	v_mov_b32_e32 v127, v35
	v_mov_b32_e32 v128, v36
	v_mov_b32_e32 v129, v37
	v_mov_b32_e32 v130, v38
	v_mov_b32_e32 v131, v39
	v_mov_b32_e32 v132, v183
	v_mov_b32_e32 v133, v177
	v_mov_b32_e32 v134, v184
	v_mov_b32_e32 v135, v185
	v_mov_b32_e32 v136, v40
	v_mov_b32_e32 v137, v41
	v_mov_b32_e32 v138, v42
	v_mov_b32_e32 v139, v43
	v_mov_b32_e32 v140, v44
	v_mov_b32_e32 v141, v45
	v_mov_b32_e32 v142, v46
	v_mov_b32_e32 v143, v47
	v_mov_b32_e32 v144, v0
	v_mov_b32_e32 v145, v1
	v_mov_b32_e32 v146, v2
	v_mov_b32_e32 v147, v3
	v_mov_b32_e32 v148, v4
	v_mov_b32_e32 v149, v5
	v_mov_b32_e32 v150, v6
	v_mov_b32_e32 v151, v7
	v_mov_b32_e32 v8, 0
	v_mov_b32_e32 v9, 0
	v_mov_b32_e32 v10, 0
	v_mov_b32_e32 v11, 0
	v_mov_b32_e32 v12, 0
	v_mov_b32_e32 v13, 0
	v_mov_b32_e32 v14, 0
	v_mov_b32_e32 v15, 0
	v_mov_b32_e32 v16, 0
	v_mov_b32_e32 v17, 0
	v_mov_b32_e32 v18, 0
	v_mov_b32_e32 v19, 0
	v_mov_b32_e32 v20, 0
	v_mov_b32_e32 v21, 0
	v_mov_b32_e32 v22, 0
	v_mov_b32_e32 v23, 0
	v_mov_b32_e32 v24, 0
	v_mov_b32_e32 v25, 0
	v_mov_b32_e32 v26, 0
	v_mov_b32_e32 v27, 0
	v_mov_b32_e32 v28, 0
	v_mov_b32_e32 v29, 0
	v_mov_b32_e32 v30, 0
	v_mov_b32_e32 v31, 0
	v_mov_b32_e32 v32, 0
	v_mov_b32_e32 v33, 0
	v_mov_b32_e32 v34, 0
	v_mov_b32_e32 v35, 0
	v_mov_b32_e32 v36, 0
	v_mov_b32_e32 v37, 0
	v_mov_b32_e32 v38, 0
	v_mov_b32_e32 v39, 0
	v_mov_b32_e32 v183, 0xf149f2ca
	v_mov_b32_e32 v177, 0xf149f2ca
	v_mov_b32_e32 v184, 0
	v_mov_b32_e32 v185, 0
	v_mov_b32_e32 v40, v228
	v_mov_b32_e32 v41, v229
	v_mov_b32_e32 v42, v230
	v_mov_b32_e32 v43, v231
	v_mov_b32_e32 v44, v232
	v_mov_b32_e32 v45, v233
	v_mov_b32_e32 v46, v234
	v_mov_b32_e32 v47, v235
	v_mov_b32_e32 v0, v236
	v_mov_b32_e32 v1, v237
	v_mov_b32_e32 v2, v238
	v_mov_b32_e32 v3, v239
	v_mov_b32_e32 v4, v240
	v_mov_b32_e32 v5, v241
	v_mov_b32_e32 v6, v242
	v_mov_b32_e32 v7, v243
	v_and_b32_e32 v152, 63, v176
	v_and_b32_e32 v153, 15, v152
	v_lshrrev_b32_e32 v154, 4, v152
	v_lshrrev_b32_e32 v155, 6, v176
	v_lshrrev_b32_e32 v156, 2, v153
	v_and_b32_e32 v157, 3, v153
	v_lshrrev_b32_e32 v158, 1, v153
	v_and_b32_e32 v159, 1, v153
	v_lshlrev_b32_e32 v160, 5, v155
	v_lshl_add_u32 v161, v156, 3, v157
	v_add_u32_e32 v161, v160, v161
	v_mul_u32_u24_e32 v161, 0x90, v161
	v_lshl_add_u32 v54, v154, 4, v161
	v_add_u32_e32 v77, 0x120, v54
	v_lshl_add_u32 v162, v154, 3, v160
	v_add_u32_e32 v163, v162, v156
	v_mul_u32_u24_e32 v163, 0x88, v163
	v_lshl_add_u32 v78, v157, 3, v163
	v_mov_b32_e32 v76, v78
	v_add_u32_e32 v74, s12, v162
	v_lshl_add_u32 v164, v158, 2, v159
	v_lshlrev_b32_e32 v165, 3, v154
	v_sub_u32_e32 v75, v165, v164
	s_mov_b32 s3, 0
; __device__ __forceinline__ float xmax16(float m) { auto rr = __builtin_amdgcn_permlane16_swap(__float_as_uint(m), __float_as_uint(m), false, false); return fmaxf(__uint_as_float(rr[0]), __uint_as_float(rr[1])); }
; __device__ __forceinline__ float xmax32(float m) { auto rr = __builtin_amdgcn_permlane32_swap(__float_as_uint(m), __float_as_uint(m), false, false); return fmaxf(__uint_as_float(rr[0]), __uint_as_float(rr[1])); }
; #define MFMA16(a, b, c) __builtin_amdgcn_mfma_f32_16x16x32_bf16((a), (b), (c), 0, 0, 0)
; __device__ __forceinline__ bf16x8 attn_softmax_step(const f32x4& sA, const f32x4& sB, int cb, int cq, int ncls, int g, float& m, float& lsum, f32x4 (&O)[4]) {
;     float s[8]; bool ok[8];
;     const int c0v = cb + 8 * g, d0 = c0v - cq + 64;
; #pragma unroll
;     for (int j = 0; j < 8; ++j) {
;         ok[j] = ((unsigned)(c0v + j) < (unsigned)ncls) && ((unsigned)(d0 + j) <= 128u);
;         s[j] = ok[j] ? (j < 4 ? sA[j] : sB[j - 4]) : -__builtin_inff(); }
;     float mx = fmaxf(fmaxf(fmaxf(s[0], s[1]), fmaxf(s[2], s[3])), fmaxf(fmaxf(s[4], s[5]), fmaxf(s[6], s[7])));
;     mx = xmax32(xmax16(mx));
;     const float mn = fmaxf(m, mx), alpha = __builtin_amdgcn_exp2f(m - mn);
;     m = mn;
;     float pj[8], ps_ = 0.f;
; #pragma unroll
;     for (int j = 0; j < 8; ++j) { pj[j] = __builtin_amdgcn_exp2f(s[j] - mn); ps_ += pj[j]; }
;     lsum = lsum * alpha + ps_;
; #pragma unroll
;     for (int nbk = 0; nbk < 4; ++nbk) O[nbk] *= alpha;
;     return pack8(pj);
; __device__ __forceinline__ void attn_lds_step(const bf16_t* Kt, const bf16_t* Vt, int rowb, const bf16x8& q0, const bf16x8& q1, int cb, int cq, int ncls,
;                                               int qi, int g, float& m, float& lsum, f32x4 (&O)[4]) {
;     const bf16_t* kA = Kt + (rowb + 8 * (qi >> 2) + (qi & 3)) * 72 + 8 * g;
;     const bf16x8 ka0 = *(const bf16x8*)kA, ka1 = *(const bf16x8*)(kA + 32), kb0 = *(const bf16x8*)(kA + 4 * 72), kb1 = *(const bf16x8*)(kA + 4 * 72 + 32);
;     f32x4 sA = {0.f, 0.f, 0.f, 0.f}, sB = {0.f, 0.f, 0.f, 0.f};
;     sA = MFMA16(ka0, q0, sA); sA = MFMA16(ka1, q1, sA);
;     sB = MFMA16(kb0, q0, sB); sB = MFMA16(kb1, q1, sB);
;     const bf16x8 P = attn_softmax_step(sA, sB, cb, cq, ncls, g, m, lsum, O);
; #pragma unroll
;     for (int nbk = 0; nbk < 4; ++nbk) O[nbk] = MFMA16(gather8(Vt + (rowb + 8 * g) * 68 + 16 * nbk, 68, qi), P, O[nbk]);
; }
.LBB0_403:
	v_add_u32_e32 v55, 0, v54
	ds_read_b128 v[48:51], v55
	ds_read_b128 v[56:59], v55 offset:64
	ds_read_b128 v[60:63], v55 offset:576
	ds_read_b128 v[64:67], v55 offset:640
	v_add_u32_e32 v55, s3, v74
	s_waitcnt lgkmcnt(3)
	v_mfma_f32_16x16x32_bf16 v[48:51], v[48:51], v[40:43], 0
	v_mov_b32_e32 v68, v183
	v_add_u32_e32 v54, 0x1200, v54
	s_waitcnt lgkmcnt(2)
	v_mfma_f32_16x16x32_bf16 v[48:51], v[56:59], v[44:47], v[48:51]
	s_waitcnt lgkmcnt(1)
	v_mfma_f32_16x16x32_bf16 v[56:59], v[60:63], v[40:43], 0
	v_subrev_u32_e32 v60, 64, v55
	v_add_u32_e32 v61, s3, v75
	v_cmp_gt_u32_e64 s[36:37], s79, v60
	v_cmp_gt_u32_e32 vcc, s78, v61
	s_and_b64 s[36:37], s[36:37], vcc
	v_cmp_gt_u32_e64 s[38:39], s90, v60
	v_add_u32_e32 v60, 1, v61
	v_cndmask_b32_e64 v48, v205, v48, s[36:37]
	v_cmp_gt_u32_e64 s[36:37], s78, v60
	v_subrev_u32_e32 v60, 62, v55
	s_and_b64 s[38:39], s[38:39], s[36:37]
	v_cmp_gt_u32_e64 s[40:41], s79, v60
	v_add_u32_e32 v60, 2, v61
	v_cndmask_b32_e64 v49, v205, v49, s[38:39]
	v_cmp_gt_u32_e64 s[38:39], s78, v60
	v_subrev_u32_e32 v60, 61, v55
	s_and_b64 s[42:43], s[40:41], s[38:39]
	v_cmp_gt_u32_e64 s[44:45], s79, v60
	v_add_u32_e32 v60, 3, v61
	s_waitcnt lgkmcnt(0)
	v_mfma_f32_16x16x32_bf16 v[56:59], v[64:67], v[44:47], v[56:59]
	v_cndmask_b32_e64 v50, v205, v50, s[42:43]
	v_cmp_gt_u32_e64 s[42:43], s78, v60
	v_subrev_u32_e32 v60, 60, v55
	s_and_b64 s[46:47], s[44:45], s[42:43]
	v_cmp_gt_u32_e64 s[48:49], s79, v60
	v_add_u32_e32 v60, 4, v61
	v_cndmask_b32_e64 v51, v205, v51, s[46:47]
	v_cmp_gt_u32_e64 s[46:47], s78, v60
	s_and_b64 s[50:51], s[48:49], s[46:47]
	v_cndmask_b32_e64 v63, v205, v56, s[50:51]
	v_subrev_u32_e32 v56, 59, v55
	v_cmp_gt_u32_e64 s[52:53], s79, v56
	v_add_u32_e32 v56, 5, v61
	v_cmp_gt_u32_e64 s[50:51], s78, v56
	v_subrev_u32_e32 v56, 58, v55
	s_and_b64 s[54:55], s[52:53], s[50:51]
	v_cmp_gt_u32_e64 s[58:59], s79, v56
	v_add_u32_e32 v56, 6, v61
	v_cndmask_b32_e64 v57, v205, v57, s[54:55]
	v_cmp_gt_u32_e64 s[54:55], s78, v56
	v_subrev_u32_e32 v56, 57, v55
	s_and_b64 s[56:57], s[58:59], s[54:55]
	v_cmp_gt_u32_e64 s[60:61], s79, v56
	v_add_u32_e32 v56, 7, v61
	v_cndmask_b32_e64 v65, v205, v58, s[56:57]
	v_cmp_gt_u32_e64 s[56:57], s78, v56
	s_and_b64 s[64:65], s[60:61], s[56:57]
	v_cndmask_b32_e64 v59, v205, v59, s[64:65]
	v_max_f32_e32 v56, v48, v49
	v_max_f32_e32 v58, v50, v51
	v_max_f32_e32 v60, v65, v59
	v_max3_f32 v60, v63, v57, v60
	v_max3_f32 v56, v56, v58, v60
	v_mov_b32_e32 v58, v56
	s_nop 1
	v_permlane16_swap_b32_e32 v56, v58
	v_max_f32_e32 v56, v56, v58
	v_mov_b32_e32 v58, v56
	s_nop 1
	v_permlane32_swap_b32_e32 v56, v58
	v_max3_f32 v183, v68, v56, v58
	v_sub_f32_e32 v48, v48, v183
	v_exp_f32_e32 v56, v48
	v_sub_f32_e32 v48, v49, v183
	v_exp_f32_e32 v58, v48
	v_sub_f32_e32 v48, v50, v183
	v_exp_f32_e32 v60, v48
	v_sub_f32_e32 v48, v51, v183
	v_exp_f32_e32 v62, v48
	v_sub_f32_e32 v48, v63, v183
	v_exp_f32_e32 v64, v48
	v_sub_f32_e32 v48, v57, v183
	v_exp_f32_e32 v66, v48
	v_sub_f32_e32 v48, v65, v183
	v_sub_f32_e32 v61, v68, v183
	v_exp_f32_e32 v68, v48
	v_sub_f32_e32 v48, v59, v183
	v_exp_f32_e32 v70, v48
	v_exp_f32_e32 v72, v61
	v_add_u32_e32 v57, 0, v78
	ds_read_b64_tr_b16 v[82:83], v57 offset:58144
	ds_read_b64_tr_b16 v[80:81], v57 offset:57600
	ds_read_b64_tr_b16 v[84:85], v57 offset:57632
	v_cvt_pk_bf16_f32 v48, v56, v58
	v_pk_mul_f32 v[30:31], v[30:31], v[72:73] op_sel_hi:[1,0]
	v_pk_mul_f32 v[28:29], v[28:29], v[72:73] op_sel_hi:[1,0]
	v_cvt_pk_bf16_f32 v49, v60, v62
	v_cvt_pk_bf16_f32 v50, v64, v66
	v_cvt_pk_bf16_f32 v51, v68, v70
	ds_read_b64_tr_b16 v[86:87], v57 offset:58176
	v_pk_mul_f32 v[34:35], v[34:35], v[72:73] op_sel_hi:[1,0]
	s_waitcnt lgkmcnt(2)
	v_mfma_f32_16x16x32_bf16 v[28:31], v[80:83], v[48:51], v[28:31]
	ds_read_b64_tr_b16 v[80:81], v57 offset:57664
	ds_read_b64_tr_b16 v[82:83], v57 offset:58208
	v_pk_mul_f32 v[32:33], v[32:33], v[72:73] op_sel_hi:[1,0]
	v_pk_mul_f32 v[26:27], v[26:27], v[72:73] op_sel_hi:[1,0]
	v_pk_mul_f32 v[24:25], v[24:25], v[72:73] op_sel_hi:[1,0]
	s_waitcnt lgkmcnt(0)
	v_mfma_f32_16x16x32_bf16 v[32:35], v[80:83], v[48:51], v[32:35]
	ds_read_b64_tr_b16 v[80:81], v57 offset:57696
	ds_read_b64_tr_b16 v[82:83], v57 offset:58240
	v_pk_mul_f32 v[38:39], v[38:39], v[72:73] op_sel_hi:[1,0]
	v_pk_mul_f32 v[36:37], v[36:37], v[72:73] op_sel_hi:[1,0]
	v_add_u32_e32 v57, 0, v77
	v_mfma_f32_16x16x32_bf16 v[24:27], v[84:87], v[48:51], v[24:27]
	s_and_b64 vcc, s[40:41], vcc
	s_add_i32 s3, s3, 32
	v_add_u32_e32 v77, 0x1200, v77
	s_waitcnt lgkmcnt(0)
	v_mfma_f32_16x16x32_bf16 v[36:39], v[80:83], v[48:51], v[36:39]
	ds_read_b128 v[48:51], v57
	ds_read_b128 v[80:83], v57 offset:64
	ds_read_b128 v[84:87], v57 offset:576
	ds_read_b128 v[88:91], v57 offset:640
	v_subrev_u32_e32 v57, 56, v55
	v_subrev_u32_e32 v55, 55, v55
	s_waitcnt lgkmcnt(3)
	v_mfma_f32_16x16x32_bf16 v[48:51], v[48:51], v[0:3], 0
	v_add_u32_e32 v78, 0x1100, v78
	s_waitcnt lgkmcnt(2)
	v_mfma_f32_16x16x32_bf16 v[48:51], v[80:83], v[4:7], v[48:51]
	s_waitcnt lgkmcnt(1)
	v_mfma_f32_16x16x32_bf16 v[80:83], v[84:87], v[0:3], 0
	s_waitcnt lgkmcnt(0)
; #define MFMA16(a, b, c) __builtin_amdgcn_mfma_f32_16x16x32_bf16((a), (b), (c), 0, 0, 0)
; __device__ __forceinline__ bf16x8 attn_softmax_step(const f32x4& sA, const f32x4& sB, int cb, int cq, int ncls, int g, float& m, float& lsum, f32x4 (&O)[4]) {
;     float s[8]; bool ok[8];
;     const int c0v = cb + 8 * g, d0 = c0v - cq + 64;
; #pragma unroll
;     for (int j = 0; j < 8; ++j) {
;         ok[j] = ((unsigned)(c0v + j) < (unsigned)ncls) && ((unsigned)(d0 + j) <= 128u);
;         s[j] = ok[j] ? (j < 4 ? sA[j] : sB[j - 4]) : -__builtin_inff(); }
;     float mx = fmaxf(fmaxf(fmaxf(s[0], s[1]), fmaxf(s[2], s[3])), fmaxf(fmaxf(s[4], s[5]), fmaxf(s[6], s[7])));
;     mx = xmax32(xmax16(mx));
;     const float mn = fmaxf(m, mx), alpha = __builtin_amdgcn_exp2f(m - mn);
;     m = mn;
;     float pj[8], ps_ = 0.f;
; #pragma unroll
;     for (int j = 0; j < 8; ++j) { pj[j] = __builtin_amdgcn_exp2f(s[j] - mn); ps_ += pj[j]; }
;     lsum = lsum * alpha + ps_;
; #pragma unroll
;     for (int nbk = 0; nbk < 4; ++nbk) O[nbk] *= alpha;
;     return pack8(pj);
; }
; __device__ __forceinline__ void attn_lds_step(const bf16_t* Kt, const bf16_t* Vt, int rowb, const bf16x8& q0, const bf16x8& q1, int cb, int cq, int ncls,
;                                               int qi, int g, float& m, float& lsum, f32x4 (&O)[4]) {
;     const bf16_t* kA = Kt + (rowb + 8 * (qi >> 2) + (qi & 3)) * 72 + 8 * g;
;     const bf16x8 ka0 = *(const bf16x8*)kA, ka1 = *(const bf16x8*)(kA + 32), kb0 = *(const bf16x8*)(kA + 4 * 72), kb1 = *(const bf16x8*)(kA + 4 * 72 + 32);
;     f32x4 sA = {0.f, 0.f, 0.f, 0.f}, sB = {0.f, 0.f, 0.f, 0.f};
;     sA = MFMA16(ka0, q0, sA); sA = MFMA16(ka1, q1, sA);
;     sB = MFMA16(kb0, q0, sB); sB = MFMA16(kb1, q1, sB);
;     const bf16x8 P = attn_softmax_step(sA, sB, cb, cq, ncls, g, m, lsum, O);
; #pragma unroll
;     for (int nbk = 0; nbk < 4; ++nbk) O[nbk] = MFMA16(gather8(Vt + (rowb + 8 * g) * 68 + 16 * nbk, 68, qi), P, O[nbk]);
; }
; __device__ __forceinline__ void attn_item(const bf16_t* __restrict__ Z, const bf16_t* __restrict__ KA, const bf16_t* __restrict__ VA, bf16_t* __restrict__ MIX, int S, int it) {
;     ...
; #pragma unroll 1
;     for (int i2 = 0; i2 < 12; ++i2) {
;         attn_lds_step(Kt, Vt, rt[0] + 32 * i2, q0[0], q1[0], P0 + rt[0] - 64 + 32 * i2, P0 + rt[0] + 16 * qi, S, qi, g, m[0], lsum[0], O[0]);
	v_mfma_f32_16x16x32_bf16 v[80:83], v[88:91], v[4:7], v[80:83]
	s_nop 3
	v_cndmask_b32_e32 v48, v205, v48, vcc
	s_and_b64 vcc, s[44:45], s[36:37]
	v_cndmask_b32_e32 v49, v205, v49, vcc
	s_and_b64 vcc, s[48:49], s[38:39]
	v_cndmask_b32_e32 v50, v205, v50, vcc
	s_and_b64 vcc, s[52:53], s[42:43]
	v_cndmask_b32_e32 v51, v205, v51, vcc
	s_and_b64 vcc, s[58:59], s[46:47]
	v_cndmask_b32_e32 v65, v205, v80, vcc
	s_and_b64 vcc, s[60:61], s[50:51]
	v_cndmask_b32_e32 v67, v205, v81, vcc
	v_cmp_gt_u32_e32 vcc, s79, v57
	s_and_b64 vcc, vcc, s[54:55]
	v_cndmask_b32_e32 v69, v205, v82, vcc
	v_cmp_gt_u32_e32 vcc, s79, v55
	s_and_b64 vcc, vcc, s[56:57]
	v_cndmask_b32_e32 v55, v205, v83, vcc
	v_max_f32_e32 v57, v48, v49
	v_max_f32_e32 v59, v50, v51
	v_max_f32_e32 v61, v69, v55
	v_max3_f32 v61, v65, v67, v61
	v_max3_f32 v57, v57, v59, v61
	v_mov_b32_e32 v59, v57
	s_nop 1
	v_permlane16_swap_b32_e32 v57, v59
	v_max_f32_e32 v57, v57, v59
	v_mov_b32_e32 v59, v57
	s_nop 1
	v_permlane32_swap_b32_e32 v57, v59
	v_mov_b32_e32 v61, v177
	v_max3_f32 v177, v61, v57, v59
	v_sub_f32_e32 v48, v48, v177
	v_exp_f32_e32 v57, v48
	v_sub_f32_e32 v48, v49, v177
	v_exp_f32_e32 v59, v48
	v_sub_f32_e32 v48, v50, v177
	v_sub_f32_e32 v73, v61, v177
	v_exp_f32_e32 v61, v48
	v_sub_f32_e32 v48, v51, v177
	v_exp_f32_e32 v63, v48
	v_sub_f32_e32 v48, v65, v177
	v_exp_f32_e32 v65, v48
	v_sub_f32_e32 v48, v67, v177
	v_exp_f32_e32 v67, v48
	v_sub_f32_e32 v48, v69, v177
	v_exp_f32_e32 v69, v48
	v_sub_f32_e32 v48, v55, v177
	v_exp_f32_e32 v71, v48
	v_pk_add_f32 v[48:49], v[56:57], 0 op_sel_hi:[1,0]
	v_exp_f32_e32 v73, v73
	v_pk_add_f32 v[48:49], v[58:59], v[48:49]
	v_add_u32_e32 v55, 0, v76
	v_pk_add_f32 v[48:49], v[60:61], v[48:49]
	v_cvt_pk_bf16_f32 v50, v65, v67
	v_pk_add_f32 v[48:49], v[62:63], v[48:49]
	v_cvt_pk_bf16_f32 v51, v69, v71
	v_pk_add_f32 v[48:49], v[64:65], v[48:49]
	v_add_u32_e32 v76, 0x1100, v76
	v_pk_add_f32 v[48:49], v[66:67], v[48:49]
	s_cmpk_eq_i32 s3, 0xa0
	v_pk_add_f32 v[48:49], v[68:69], v[48:49]
	s_nop 0
	v_pk_add_f32 v[48:49], v[70:71], v[48:49]
	s_nop 0
	v_pk_fma_f32 v[184:185], v[184:185], v[72:73], v[48:49]
	v_mov_b32_e32 v48, v73
	v_pk_mul_f32 v[18:19], v[18:19], v[48:49] op_sel_hi:[1,0]
	v_pk_mul_f32 v[16:17], v[16:17], v[48:49] op_sel_hi:[1,0]
	v_pk_mul_f32 v[10:11], v[10:11], v[48:49] op_sel_hi:[1,0]
	v_pk_mul_f32 v[8:9], v[8:9], v[48:49] op_sel_hi:[1,0]
	v_pk_mul_f32 v[22:23], v[22:23], v[48:49] op_sel_hi:[1,0]
	v_pk_mul_f32 v[20:21], v[20:21], v[48:49] op_sel_hi:[1,0]
	v_pk_mul_f32 v[14:15], v[14:15], v[48:49] op_sel_hi:[1,0]
	v_pk_mul_f32 v[12:13], v[12:13], v[48:49] op_sel_hi:[1,0]
	v_cvt_pk_bf16_f32 v48, v57, v59
	v_cvt_pk_bf16_f32 v49, v61, v63
	ds_read_b64_tr_b16 v[58:59], v55 offset:58416
	ds_read_b64_tr_b16 v[56:57], v55 offset:57872
	ds_read_b64_tr_b16 v[60:61], v55 offset:57904
	s_waitcnt lgkmcnt(1)
	v_mfma_f32_16x16x32_bf16 v[16:19], v[56:59], v[48:51], v[16:19]
	ds_read_b64_tr_b16 v[62:63], v55 offset:58448
	ds_read_b64_tr_b16 v[56:57], v55 offset:57936
	ds_read_b64_tr_b16 v[58:59], v55 offset:58480
	s_waitcnt lgkmcnt(0)
	v_mfma_f32_16x16x32_bf16 v[20:23], v[56:59], v[48:51], v[20:23]
	ds_read_b64_tr_b16 v[56:57], v55 offset:57968
	ds_read_b64_tr_b16 v[58:59], v55 offset:58512
	v_mfma_f32_16x16x32_bf16 v[8:11], v[60:63], v[48:51], v[8:11]
	s_waitcnt lgkmcnt(0)
	v_mfma_f32_16x16x32_bf16 v[12:15], v[56:59], v[48:51], v[12:15]
	s_cbranch_scc0 .LBB0_403
	v_mov_b32_e32 v152, v184
	s_nop 1
	v_permlane16_swap_b32_e32 v184, v152
	v_add_f32_e32 v152, v184, v152
	v_mov_b32_e32 v153, v152
	s_nop 1
	v_permlane32_swap_b32_e32 v152, v153
	v_add_f32_e32 v152, v152, v153
	v_mov_b32_e32 v154, v185
	s_nop 1
	v_permlane16_swap_b32_e32 v185, v154
	v_add_f32_e32 v154, v185, v154
	v_mov_b32_e32 v155, v154
	s_nop 1
	v_permlane32_swap_b32_e32 v154, v155
	v_add_f32_e32 v154, v154, v155
	v_and_b32_e32 v156, 63, v176
	v_and_b32_e32 v157, 15, v156
	v_lshrrev_b32_e32 v158, 4, v156
	v_lshrrev_b32_e32 v159, 6, v176
	v_lshrrev_b32_e32 v160, 1, v157
	v_and_b32_e32 v161, 1, v157
	v_lshl_add_u32 v160, v160, 2, v161
	v_lshl_add_u32 v160, v159, 5, v160
	v_mul_u32_u24_e32 v161, 0x110, v160
	v_lshl_add_u32 v161, v158, 4, v161
	v_lshlrev_b32_e32 v162, 2, v160
	v_add_u32_e32 v162, 0x11000, v162
	v_lshrrev_b32_e32 v163, 1, v159
	v_and_b32_e32 v164, 1, v159
	v_lshl_add_u32 v163, v163, 2, v164
	v_lshl_add_u32 v163, v157, 4, v163
	v_mul_u32_u24_e32 v164, 0x110, v163
	v_lshl_add_u32 v164, v158, 4, v164
	v_lshlrev_b32_e32 v165, 2, v163
	v_add_u32_e32 v165, 0x11000, v165
	s_barrier
	ds_write_b128 v161, v[28:31]
	ds_write_b128 v161, v[24:27] offset:64
	ds_write_b128 v161, v[32:35] offset:128
	ds_write_b128 v161, v[36:39] offset:192
	ds_write_b128 v161, v[16:19] offset:544
	ds_write_b128 v161, v[8:11] offset:608
	ds_write_b128 v161, v[20:23] offset:672
	ds_write_b128 v161, v[12:15] offset:736
	ds_write_b32 v162, v183
	ds_write_b32 v162, v177 offset:8
	ds_write_b32 v162, v152 offset:1024
	ds_write_b32 v162, v154 offset:1032
	s_waitcnt lgkmcnt(0)
	s_barrier
; template <int NROWS>
; __device__ __forceinline__ void attn_stage(const bf16_t* __restrict__ ka, const bf16_t* __restrict__ va, bf16_t* Kt, bf16_t* Vt, int c0, int ncls, int rd, int dsh, int tid) {
;     ...
;     for (int u = 0; u < IT; ++u) { const int idx = min(tid + u * NTHR, NROWS * 16 - 1);
;         const int i = idx >> 4, ch = idx & 15, isv = ch >> 3, c8 = ch & 7; const int c = min(max(c0 + i, 0), ncls - 1);
;         v[u] = *(const u32x4*)((isv ? va : ka) + (size_t)(rd + (c << dsh)) * 64 + 8 * c8); }
; __device__ __forceinline__ void attn_item(const bf16_t* __restrict__ Z, const bf16_t* __restrict__ KA, const bf16_t* __restrict__ VA, bf16_t* __restrict__ MIX, int S, int it) {
;     ...
;     for (int i2 = 0; i2 < 12; ++i2) {
;         attn_lds_step(Kt, Vt, rt[0] + 32 * i2, q0[0], q1[0], P0 + rt[0] - 64 + 32 * i2, P0 + rt[0] + 16 * qi, S, qi, g, m[0], lsum[0], O[0]);
;         attn_lds_step(Kt, Vt, rt[1] + 32 * i2, q0[1], q1[1], P0 + rt[1] - 64 + 32 * i2, P0 + rt[1] + 16 * qi, S, qi, g, m[1], lsum[1], O[1]);
;     }
; #pragma unroll
;     for (int rho = 0; rho < 2; ++rho) {
;         __syncthreads();
;         attn_stage<200>(ka, va, Kt, Vt, (P0 >> 2) - 64, S >> 2, 2 * rho, 2, tid);
;         attn_stage<200>(ka, va, Kt + 200 * 72, Vt + 200 * 68, (P0 >> 2) - 64, S >> 2, 2 * rho + 1, 2, tid);
;         __syncthreads();
;         const int r = rt[rho], cls = (r & 3) - 2 * rho, c0 = (P0 >> 2) + (r >> 2);
	ds_read_b128 v[216:219], v164
	ds_read_b128 v[220:223], v164 offset:64
	ds_read_b128 v[224:227], v164 offset:128
	ds_read_b128 v[228:231], v164 offset:192
	ds_read_b128 v[232:235], v164 offset:544
	ds_read_b128 v[236:239], v164 offset:608
	ds_read_b128 v[240:243], v164 offset:672
	ds_read_b128 v[244:247], v164 offset:736
	ds_read_b32 v248, v165
	ds_read_b32 v249, v165 offset:8
	ds_read_b32 v250, v165 offset:1024
	ds_read_b32 v251, v165 offset:1032
	v_mov_b32_e32 v8, v100
	v_mov_b32_e32 v9, v101
	v_mov_b32_e32 v10, v102
	v_mov_b32_e32 v11, v103
	v_mov_b32_e32 v12, v104
	v_mov_b32_e32 v13, v105
	v_mov_b32_e32 v14, v106
	v_mov_b32_e32 v15, v107
	v_mov_b32_e32 v16, v108
	v_mov_b32_e32 v17, v109
	v_mov_b32_e32 v18, v110
	v_mov_b32_e32 v19, v111
	v_mov_b32_e32 v20, v112
	v_mov_b32_e32 v21, v113
	v_mov_b32_e32 v22, v114
	v_mov_b32_e32 v23, v115
	v_mov_b32_e32 v24, v116
	v_mov_b32_e32 v25, v117
	v_mov_b32_e32 v26, v118
	v_mov_b32_e32 v27, v119
	v_mov_b32_e32 v28, v120
	v_mov_b32_e32 v29, v121
	v_mov_b32_e32 v30, v122
	v_mov_b32_e32 v31, v123
	v_mov_b32_e32 v32, v124
	v_mov_b32_e32 v33, v125
	v_mov_b32_e32 v34, v126
	v_mov_b32_e32 v35, v127
	v_mov_b32_e32 v36, v128
	v_mov_b32_e32 v37, v129
	v_mov_b32_e32 v38, v130
	v_mov_b32_e32 v39, v131
	v_mov_b32_e32 v183, v132
	v_mov_b32_e32 v177, v133
	v_mov_b32_e32 v184, v134
	v_mov_b32_e32 v185, v135
	v_mov_b32_e32 v40, v136
	v_mov_b32_e32 v41, v137
	v_mov_b32_e32 v42, v138
	v_mov_b32_e32 v43, v139
	v_mov_b32_e32 v44, v140
	v_mov_b32_e32 v45, v141
	v_mov_b32_e32 v46, v142
	v_mov_b32_e32 v47, v143
	v_mov_b32_e32 v0, v144
	v_mov_b32_e32 v1, v145
	v_mov_b32_e32 v2, v146
	v_mov_b32_e32 v3, v147
	v_mov_b32_e32 v4, v148
	v_mov_b32_e32 v5, v149
	v_mov_b32_e32 v6, v150
	v_mov_b32_e32 v7, v151
	s_waitcnt lgkmcnt(0)
	v_max_f32_e32 v166, v183, v248
	v_sub_f32_e32 v167, v183, v166
	v_sub_f32_e32 v168, v248, v166
	v_exp_f32_e32 v167, v167
	v_exp_f32_e32 v168, v168
	v_max_f32_e32 v170, v177, v249
	v_sub_f32_e32 v171, v177, v170
	v_sub_f32_e32 v172, v249, v170
	v_exp_f32_e32 v171, v171
	v_exp_f32_e32 v172, v172
	v_mov_b32_e32 v183, v166
	v_mov_b32_e32 v177, v170
	v_mul_f32_e32 v169, 0x3e800000, v250
	v_mul_f32_e32 v152, 0x3e800000, v251
	v_mul_f32_e32 v184, v184, v167
	v_fmac_f32_e32 v184, v169, v168
	v_mul_f32_e32 v185, v185, v171
	v_fmac_f32_e32 v185, v152, v172
	v_mul_f32_e32 v28, v28, v167
	v_fmac_f32_e32 v28, v216, v168
	v_mul_f32_e32 v29, v29, v167
	v_fmac_f32_e32 v29, v217, v168
	v_mul_f32_e32 v30, v30, v167
	v_fmac_f32_e32 v30, v218, v168
	v_mul_f32_e32 v31, v31, v167
	v_fmac_f32_e32 v31, v219, v168
	v_mul_f32_e32 v24, v24, v167
	v_fmac_f32_e32 v24, v220, v168
	v_mul_f32_e32 v25, v25, v167
	v_fmac_f32_e32 v25, v221, v168
	v_mul_f32_e32 v26, v26, v167
	v_fmac_f32_e32 v26, v222, v168
	v_mul_f32_e32 v27, v27, v167
	v_fmac_f32_e32 v27, v223, v168
	v_mul_f32_e32 v32, v32, v167
	v_fmac_f32_e32 v32, v224, v168
	v_mul_f32_e32 v33, v33, v167
	v_fmac_f32_e32 v33, v225, v168
	v_mul_f32_e32 v34, v34, v167
	v_fmac_f32_e32 v34, v226, v168
	v_mul_f32_e32 v35, v35, v167
	v_fmac_f32_e32 v35, v227, v168
	v_mul_f32_e32 v36, v36, v167
	v_fmac_f32_e32 v36, v228, v168
	v_mul_f32_e32 v37, v37, v167
	v_fmac_f32_e32 v37, v229, v168
	v_mul_f32_e32 v38, v38, v167
	v_fmac_f32_e32 v38, v230, v168
	v_mul_f32_e32 v39, v39, v167
	v_fmac_f32_e32 v39, v231, v168
	v_mul_f32_e32 v16, v16, v171
	v_fmac_f32_e32 v16, v232, v172
	v_mul_f32_e32 v17, v17, v171
	v_fmac_f32_e32 v17, v233, v172
	v_mul_f32_e32 v18, v18, v171
	v_fmac_f32_e32 v18, v234, v172
	v_mul_f32_e32 v19, v19, v171
	v_fmac_f32_e32 v19, v235, v172
	v_mul_f32_e32 v8, v8, v171
	v_fmac_f32_e32 v8, v236, v172
	v_mul_f32_e32 v9, v9, v171
	v_fmac_f32_e32 v9, v237, v172
	v_mul_f32_e32 v10, v10, v171
	v_fmac_f32_e32 v10, v238, v172
	v_mul_f32_e32 v11, v11, v171
	v_fmac_f32_e32 v11, v239, v172
	v_mul_f32_e32 v20, v20, v171
	v_fmac_f32_e32 v20, v240, v172
	v_mul_f32_e32 v21, v21, v171
	v_fmac_f32_e32 v21, v241, v172
	v_mul_f32_e32 v22, v22, v171
	v_fmac_f32_e32 v22, v242, v172
	v_mul_f32_e32 v23, v23, v171
	v_fmac_f32_e32 v23, v243, v172
	v_mul_f32_e32 v12, v12, v171
	v_fmac_f32_e32 v12, v244, v172
	v_mul_f32_e32 v13, v13, v171
	v_fmac_f32_e32 v13, v245, v172
	v_mul_f32_e32 v14, v14, v171
	v_fmac_f32_e32 v14, v246, v172
	v_mul_f32_e32 v15, v15, v171
	v_fmac_f32_e32 v15, v247, v172
	s_lshl_b32 s18, s2, 6
	v_min_i32_e32 v50, 0xc7f, v187
	s_sub_i32 s2, s18, 64
	v_ashrrev_i32_e32 v59, 4, v50
	v_add_u32_e32 v48, s2, v59
	v_max_i32_e32 v48, 0, v48
	v_readlane_b32 s3, v255, 38
	v_mov_b32_e32 v63, s95
	v_mov_b32_e32 v67, s7
	v_min_u32_e32 v51, s3, v48
	v_and_b32_e32 v48, 8, v50
	v_cmp_eq_u32_e32 vcc, 0, v48
	v_mov_b32_e32 v71, s94
	v_mov_b32_e32 v75, s6
	v_lshlrev_b32_e32 v50, 4, v50
	v_cndmask_b32_e32 v49, v63, v67, vcc
	v_cndmask_b32_e32 v48, v71, v75, vcc
	v_and_b32_e32 v178, 0x70, v50
	v_lshl_add_u64 v[56:57], v[48:49], 0, v[178:179]
	v_min_i32_e32 v48, 0xa7f, v187
	v_add_u32_e32 v49, 0x200, v48
	v_ashrrev_i32_e32 v79, 4, v49
	v_add_u32_e32 v49, s2, v79
	v_max_i32_e32 v49, 0, v49
	v_and_b32_e32 v50, 8, v48
	v_min_u32_e32 v49, s3, v49
	v_cmp_eq_u32_e64 s[36:37], 0, v50
	v_lshlrev_b32_e32 v48, 4, v48
	v_lshlrev_b32_e32 v58, 2, v51
	v_cndmask_b32_e64 v51, v63, v67, s[36:37]
	v_cndmask_b32_e64 v50, v71, v75, s[36:37]
	v_lshlrev_b32_e32 v62, 2, v49
	v_and_b32_e32 v48, 0x70, v48
	v_mov_b32_e32 v49, v179
	v_lshl_add_u64 v[60:61], v[50:51], 0, v[48:49]
	v_min_i32_e32 v49, 0x87f, v187
	v_add_u32_e32 v50, 0x400, v49
	v_ashrrev_i32_e32 v83, 4, v50
	v_add_u32_e32 v50, s2, v83
	v_max_i32_e32 v50, 0, v50
	v_and_b32_e32 v51, 8, v49
	v_min_u32_e32 v50, s3, v50
	v_cmp_eq_u32_e64 s[38:39], 0, v51
	v_lshlrev_b32_e32 v49, 4, v49
; template <int NROWS>
; __device__ __forceinline__ void attn_stage(const bf16_t* __restrict__ ka, const bf16_t* __restrict__ va, bf16_t* Kt, bf16_t* Vt, int c0, int ncls, int rd, int dsh, int tid) {
;     ...
;     for (int u = 0; u < IT; ++u) { const int idx = min(tid + u * NTHR, NROWS * 16 - 1);
;         const int i = idx >> 4, ch = idx & 15, isv = ch >> 3, c8 = ch & 7; const int c = min(max(c0 + i, 0), ncls - 1);
;         v[u] = *(const u32x4*)((isv ? va : ka) + (size_t)(rd + (c << dsh)) * 64 + 8 * c8); }
; #pragma unroll
;     for (int u = 0; u < IT; ++u) { const int idx = min(tid + u * NTHR, NROWS * 16 - 1);
;         const int i = idx >> 4, ch = idx & 15, isv = ch >> 3, c8 = ch & 7;
;         bf16_t* d = isv ? (Vt + i * 68 + 8 * c8) : (Kt + i * 72 + 8 * c8);
;         *(u32x2*)d = (u32x2){v[u].x, v[u].y}; *(u32x2*)(d + 4) = (u32x2){v[u].z, v[u].w}; }
; __device__ __forceinline__ void attn_item(const bf16_t* __restrict__ Z, const bf16_t* __restrict__ KA, const bf16_t* __restrict__ VA, bf16_t* __restrict__ MIX, int S, int it) {
;     ...
;         __syncthreads();
;         attn_stage<200>(ka, va, Kt, Vt, (P0 >> 2) - 64, S >> 2, 2 * rho, 2, tid);
;         attn_stage<200>(ka, va, Kt + 200 * 72, Vt + 200 * 68, (P0 >> 2) - 64, S >> 2, 2 * rho + 1, 2, tid);
	v_lshlrev_b32_e32 v66, 2, v50
	v_cndmask_b32_e64 v55, v63, v67, s[38:39]
	v_cndmask_b32_e64 v54, v71, v75, s[38:39]
	v_and_b32_e32 v50, 0x70, v49
	v_mov_b32_e32 v51, v179
	v_min_i32_e32 v49, 0x67f, v187
	v_lshl_add_u64 v[64:65], v[54:55], 0, v[50:51]
	v_add_u32_e32 v51, 0x600, v49
	v_ashrrev_i32_e32 v90, 4, v51
	v_add_u32_e32 v51, s2, v90
	v_max_i32_e32 v51, 0, v51
	v_and_b32_e32 v54, 8, v49
	v_lshlrev_b32_e32 v49, 4, v49
	v_min_u32_e32 v51, s3, v51
	v_cmp_eq_u32_e64 s[40:41], 0, v54
	v_and_b32_e32 v54, 0x70, v49
	v_min_i32_e32 v49, 0x47f, v187
	v_lshlrev_b32_e32 v70, 2, v51
	v_add_u32_e32 v51, 0x800, v49
	v_ashrrev_i32_e32 v91, 4, v51
	v_cndmask_b32_e64 v69, v63, v67, s[40:41]
	v_cndmask_b32_e64 v68, v71, v75, s[40:41]
	v_mov_b32_e32 v55, v179
	v_add_u32_e32 v51, s2, v91
	v_lshl_add_u64 v[68:69], v[68:69], 0, v[54:55]
	v_max_i32_e32 v51, 0, v51
	v_and_b32_e32 v55, 8, v49
	v_lshlrev_b32_e32 v49, 4, v49
	v_min_u32_e32 v51, s3, v51
	v_and_b32_e32 v84, 0x70, v49
	v_min_i32_e32 v49, 0x27f, v187
	v_lshlrev_b32_e32 v74, 2, v51
	v_add_u32_e32 v51, 0xa00, v49
	v_ashrrev_i32_e32 v92, 4, v51
	v_add_u32_e32 v51, s2, v92
	v_cmp_eq_u32_e64 s[42:43], 0, v55
	v_max_i32_e32 v51, 0, v51
	v_and_b32_e32 v55, 8, v49
	v_lshlrev_b32_e32 v49, 4, v49
	v_min_u32_e32 v51, s3, v51
	v_and_b32_e32 v86, 0x70, v49
	v_min_i32_e32 v49, 0x7f, v187
	v_lshlrev_b32_e32 v78, 2, v51
	v_add_u32_e32 v51, 0xc00, v49
	v_ashrrev_i32_e32 v93, 4, v51
	v_cmp_eq_u32_e64 s[44:45], 0, v55
	v_add_u32_e32 v51, s2, v93
	v_and_b32_e32 v55, 8, v49
	v_lshlrev_b32_e32 v49, 4, v49
	v_max_i32_e32 v51, 0, v51
	v_cmp_eq_u32_e64 s[46:47], 0, v55
	v_and_b32_e32 v88, 0x70, v49
	v_cndmask_b32_e32 v49, v206, v207, vcc
	v_readlane_b32 s2, v255, 0
	v_cndmask_b32_e64 v72, v71, v75, s[42:43]
	v_cndmask_b32_e64 v76, v71, v75, s[44:45]
	v_min_u32_e32 v51, s3, v51
	v_cndmask_b32_e64 v80, v71, v75, s[46:47]
	v_mov_b32_e32 v71, s2
	v_mul_lo_u32 v49, v49, v59
	v_cndmask_b32_e64 v73, v63, v67, s[42:43]
	v_mov_b32_e32 v85, v179
	v_lshlrev_b32_e32 v82, 2, v51
	v_cndmask_b32_e64 v51, v71, 0, vcc
	v_lshlrev_b32_e32 v49, 1, v49
	v_lshl_add_u64 v[72:73], v[72:73], 0, v[84:85]
	v_add3_u32 v85, v51, v49, v178
	v_cndmask_b32_e64 v51, v206, v207, s[36:37]
	v_mul_lo_u32 v51, v51, v79
	v_cndmask_b32_e64 v77, v63, v67, s[44:45]
	v_mov_b32_e32 v87, v179
	v_cndmask_b32_e64 v55, v71, 0, s[36:37]
	v_lshlrev_b32_e32 v51, 1, v51
	v_lshl_add_u64 v[76:77], v[76:77], 0, v[86:87]
	v_add3_u32 v87, v55, v51, v48
	v_cndmask_b32_e64 v55, v206, v207, s[38:39]
	v_mul_lo_u32 v55, v55, v83
	v_cndmask_b32_e64 v81, v63, v67, s[46:47]
	v_mov_b32_e32 v89, v179
	v_cndmask_b32_e64 v59, v71, 0, s[38:39]
	v_lshlrev_b32_e32 v55, 1, v55
	v_lshl_add_u64 v[80:81], v[80:81], 0, v[88:89]
	v_add3_u32 v89, v59, v55, v50
	v_cndmask_b32_e64 v59, v206, v207, s[40:41]
	v_mul_lo_u32 v59, v59, v90
	v_cndmask_b32_e64 v63, v71, 0, s[40:41]
	v_lshlrev_b32_e32 v59, 1, v59
	v_add3_u32 v90, v63, v59, v54
	v_cndmask_b32_e64 v63, v206, v207, s[42:43]
	v_mul_lo_u32 v63, v63, v91
	v_cndmask_b32_e64 v67, v71, 0, s[42:43]
	v_lshlrev_b32_e32 v63, 1, v63
	v_add3_u32 v91, v67, v63, v84
	v_cndmask_b32_e64 v67, v206, v207, s[44:45]
	s_mov_b64 s[2:3], src_shared_base
	s_cmp_lg_u32 0, -1
	v_mul_lo_u32 v67, v67, v92
	s_cselect_b32 s2, 0, 0
	v_cndmask_b32_e64 v75, v71, 0, s[44:45]
	v_lshlrev_b32_e32 v67, 1, v67
	s_cselect_b32 s3, s3, 0
	s_add_u32 s2, s2, 0x7080
	v_add3_u32 v92, v75, v67, v86
	v_cndmask_b32_e64 v75, v206, v207, s[46:47]
	s_addc_u32 s3, s3, 0
	v_cndmask_b32_e64 v79, v71, 0, s[46:47]
	v_mul_lo_u32 v71, v75, v93
	s_cmp_lg_u64 s[2:3], 0
	v_lshlrev_b32_e32 v71, 1, v71
	s_cselect_b32 s2, s2, -1
	s_add_i32 s3, 0, 0x14b40
	v_add3_u32 v93, v79, v71, v88
	v_mov_b32_e32 v75, s3
	v_mov_b32_e32 v79, s2
	v_cndmask_b32_e32 v83, v75, v79, vcc
	v_add3_u32 v97, v83, v49, v178
	v_cndmask_b32_e64 v49, v75, v79, s[36:37]
	v_add3_u32 v98, v49, v51, v48
	v_cndmask_b32_e64 v48, v75, v79, s[38:39]
	v_add3_u32 v99, v48, v55, v50
	v_cndmask_b32_e64 v48, v75, v79, s[40:41]
	v_add3_u32 v100, v48, v59, v54
	v_cndmask_b32_e64 v48, v75, v79, s[42:43]
	v_add3_u32 v84, v48, v63, v84
	v_mov_b32_e32 v63, v179
	v_cndmask_b32_e64 v48, v75, v79, s[44:45]
	v_lshlrev_b64 v[54:55], 7, v[62:63]
	v_add3_u32 v86, v48, v67, v86
	v_lshl_add_u64 v[54:55], v[60:61], 0, v[54:55]
	v_mov_b32_e32 v67, v179
	v_cndmask_b32_e64 v48, v75, v79, s[46:47]
	s_barrier
; template <int NROWS>
; __device__ __forceinline__ void attn_stage(const bf16_t* __restrict__ ka, const bf16_t* __restrict__ va, bf16_t* Kt, bf16_t* Vt, int c0, int ncls, int rd, int dsh, int tid) {
;     ...
;     for (int u = 0; u < IT; ++u) { const int idx = min(tid + u * NTHR, NROWS * 16 - 1);
;         const int i = idx >> 4, ch = idx & 15, isv = ch >> 3, c8 = ch & 7; const int c = min(max(c0 + i, 0), ncls - 1);
;         v[u] = *(const u32x4*)((isv ? va : ka) + (size_t)(rd + (c << dsh)) * 64 + 8 * c8); }
; #pragma unroll
;     for (int u = 0; u < IT; ++u) { const int idx = min(tid + u * NTHR, NROWS * 16 - 1);
;         const int i = idx >> 4, ch = idx & 15, isv = ch >> 3, c8 = ch & 7;
;         bf16_t* d = isv ? (Vt + i * 68 + 8 * c8) : (Kt + i * 72 + 8 * c8);
;         *(u32x2*)d = (u32x2){v[u].x, v[u].y}; *(u32x2*)(d + 4) = (u32x2){v[u].z, v[u].w}; }
; __device__ __forceinline__ void attn_item(const bf16_t* __restrict__ Z, const bf16_t* __restrict__ KA, const bf16_t* __restrict__ VA, bf16_t* __restrict__ MIX, int S, int it) {
;     ...
;         attn_stage<200>(ka, va, Kt, Vt, (P0 >> 2) - 64, S >> 2, 2 * rho, 2, tid);
;         attn_stage<200>(ka, va, Kt + 200 * 72, Vt + 200 * 68, (P0 >> 2) - 64, S >> 2, 2 * rho + 1, 2, tid);
;         __syncthreads();
;         const int r = rt[rho], cls = (r & 3) - 2 * rho, c0 = (P0 >> 2) + (r >> 2);
; #pragma unroll 2
;         for (int i2 = 0; i2 < 6; ++i2)
;             attn_lds_step(Kt + cls * 200 * 72, Vt + cls * 200 * 68, (r >> 2) + 32 * i2, q0[rho], q1[rho], c0 - 64 + 32 * i2, c0 + 4 * qi, S >> 2, qi, g, m[rho], lsum[rho], O[rho]);
	global_load_dwordx4 v[102:105], v[54:55], off
	v_lshlrev_b64 v[54:55], 7, v[66:67]
	v_add3_u32 v88, v48, v71, v88
	v_mov_b32_e32 v59, v179
	v_lshl_add_u64 v[54:55], v[64:65], 0, v[54:55]
	v_mov_b32_e32 v71, v179
	v_lshlrev_b64 v[48:49], 7, v[58:59]
	global_load_dwordx4 v[106:109], v[54:55], off
	v_lshlrev_b64 v[54:55], 7, v[70:71]
	v_lshl_add_u64 v[48:49], v[56:57], 0, v[48:49]
	v_lshl_add_u64 v[54:55], v[68:69], 0, v[54:55]
	v_mov_b32_e32 v75, v179
	global_load_dwordx4 v[48:51], v[48:49], off
	v_mov_b32_e32 v79, v179
	global_load_dwordx4 v[110:113], v[54:55], off
	v_lshlrev_b64 v[54:55], 7, v[74:75]
	v_lshl_add_u64 v[54:55], v[72:73], 0, v[54:55]
	global_load_dwordx4 v[114:117], v[54:55], off
	v_lshlrev_b64 v[54:55], 7, v[78:79]
	v_lshl_add_u64 v[54:55], v[76:77], 0, v[54:55]
	v_mov_b32_e32 v83, v179
	global_load_dwordx4 v[118:121], v[54:55], off
	v_lshlrev_b64 v[54:55], 7, v[82:83]
	v_lshl_add_u64 v[54:55], v[80:81], 0, v[54:55]
	global_load_dwordx4 v[122:125], v[54:55], off
	v_or_b32_e32 v178, 1, v58
	s_waitcnt vmcnt(4)
	ds_write2_b64 v85, v[48:49], v[50:51] offset1:1
	ds_write2_b64 v87, v[102:103], v[104:105] offset1:1
	ds_write2_b64 v89, v[106:107], v[108:109] offset1:1
	s_waitcnt vmcnt(3)
	ds_write2_b64 v90, v[110:111], v[112:113] offset1:1
	s_waitcnt vmcnt(2)
	ds_write2_b64 v91, v[114:115], v[116:117] offset1:1
	s_waitcnt vmcnt(1)
	ds_write2_b64 v92, v[118:119], v[120:121] offset1:1
	s_waitcnt vmcnt(0)
	ds_write2_b64 v93, v[122:123], v[124:125] offset1:1
	v_lshlrev_b64 v[48:49], 7, v[178:179]
	v_or_b32_e32 v178, 1, v62
	v_lshlrev_b64 v[54:55], 7, v[178:179]
	v_lshl_add_u64 v[54:55], v[60:61], 0, v[54:55]
	v_or_b32_e32 v178, 1, v66
	global_load_dwordx4 v[102:105], v[54:55], off
	v_lshlrev_b64 v[54:55], 7, v[178:179]
	v_lshl_add_u64 v[54:55], v[64:65], 0, v[54:55]
	v_or_b32_e32 v178, 1, v70
	global_load_dwordx4 v[106:109], v[54:55], off
	v_lshlrev_b64 v[54:55], 7, v[178:179]
	v_lshl_add_u64 v[48:49], v[56:57], 0, v[48:49]
	v_lshl_add_u64 v[54:55], v[68:69], 0, v[54:55]
	v_or_b32_e32 v178, 1, v74
	global_load_dwordx4 v[48:51], v[48:49], off
	v_mul_u32_u24_e32 v101, 0x88, v214
	global_load_dwordx4 v[110:113], v[54:55], off
	v_lshlrev_b64 v[54:55], 7, v[178:179]
	v_lshl_add_u64 v[54:55], v[72:73], 0, v[54:55]
	v_or_b32_e32 v178, 1, v78
	global_load_dwordx4 v[114:117], v[54:55], off
	v_lshlrev_b64 v[54:55], 7, v[178:179]
	v_lshl_add_u64 v[54:55], v[76:77], 0, v[54:55]
	v_or_b32_e32 v178, 1, v82
	global_load_dwordx4 v[118:121], v[54:55], off
	v_lshlrev_b64 v[54:55], 7, v[178:179]
	v_lshl_add_u64 v[54:55], v[80:81], 0, v[54:55]
	global_load_dwordx4 v[122:125], v[54:55], off
	s_waitcnt vmcnt(4)
	ds_write2_b64 v97, v[48:49], v[50:51] offset1:1
	ds_write2_b64 v98, v[102:103], v[104:105] offset1:1
	ds_write2_b64 v99, v[106:107], v[108:109] offset1:1
	s_waitcnt vmcnt(3)
	ds_write2_b64 v100, v[110:111], v[112:113] offset1:1
	s_waitcnt vmcnt(2)
	ds_write2_b64 v84, v[114:115], v[116:117] offset1:1
	s_waitcnt vmcnt(1)
	ds_write2_b64 v86, v[118:119], v[120:121] offset1:1
	s_waitcnt vmcnt(0)
	ds_write2_b64 v88, v[122:123], v[124:125] offset1:1
	v_ashrrev_i32_e32 v48, 7, v187
	v_mul_u32_u24_e32 v50, 0x6a40, v211
	s_movk_i32 s2, 0x88
	v_add3_u32 v50, v50, v101, v94
	v_mul_lo_u32 v51, v48, s2
	v_add3_u32 v59, v50, v51, v96
	v_add_u32_e32 v50, v48, v212
	s_movk_i32 s3, 0x90
	v_mul_u32_u24_e32 v49, 0x7080, v211
	v_mul_lo_u32 v51, v50, s3
	v_add3_u32 v67, v48, s18, v186
	v_add_u32_e32 v48, v50, v53
	v_add3_u32 v51, v49, v95, v51
	s_movk_i32 s2, 0x1200
	v_mul_lo_u32 v48, v48, s3
	v_add3_u32 v63, v51, v52, s2
	v_add3_u32 v75, v49, v48, v52
	s_mov_b32 s15, 0
	v_sub_u32_e32 v71, v186, v213
	v_mov_b32_e32 v79, v75
	v_mov_b32_e32 v83, v63
	v_mov_b32_e32 v94, v59
	s_waitcnt lgkmcnt(0)
	s_barrier
